# GEMM K-loops: priority flips inverted (raised through the load slot, lowered for the MFMA cluster), reset after each GEMM phase
# baseline (speedup 1.0000x reference)
.LBB0_262:
	ds_read_b128 v[128:131], v181
	ds_read_b128 v[132:135], v181 offset:1024
	ds_read_b128 v[136:139], v181 offset:2048
	ds_read_b128 v[140:143], v181 offset:3072
	s_add_u32 s6, s4, 0xfff80080
	s_addc_u32 s7, s5, -1
	s_cmp_eq_u32 s37, 28
	s_cselect_b32 s9, s10, s7
	s_cselect_b32 s8, s11, s6
	s_cselect_b32 s7, s20, s36
	s_cselect_b32 s6, s34, s35
	v_lshl_add_u64 v[176:177], s[4:5], 0, v[158:159]
	s_add_i32 m0, s44, 0xc000
	ds_read_b128 v[144:147], v182
	ds_read_b128 v[168:171], v182 offset:1024
	ds_read_b128 v[172:175], v182 offset:2048
	ds_read_b128 v[184:187], v182 offset:3072
	ds_read_b128 v[188:191], v182 offset:4096
	ds_read_b128 v[192:195], v182 offset:5120
	ds_read_b128 v[196:199], v182 offset:6144
	ds_read_b128 v[200:203], v182 offset:7168
	global_load_lds_dwordx4 v[176:177], off
	v_lshl_add_u64 v[176:177], s[4:5], 0, v[160:161]
	s_add_i32 m0, s44, 0xe000
	s_nop 0
	global_load_lds_dwordx4 v[176:177], off
	s_waitcnt lgkmcnt(8)
	s_barrier
	s_waitcnt lgkmcnt(0)
	s_setprio 0
	s_waitcnt lgkmcnt(0)
	v_mfma_f32_16x16x32_bf16 v[124:127], v[128:131], v[144:147], v[124:127]
	v_mfma_f32_16x16x32_bf16 v[120:123], v[136:139], v[144:147], v[120:123]
	v_mfma_f32_16x16x32_bf16 v[108:111], v[128:131], v[172:175], v[108:111]
	v_mfma_f32_16x16x32_bf16 v[104:107], v[136:139], v[172:175], v[104:107]
	v_mfma_f32_16x16x32_bf16 v[92:95], v[128:131], v[188:191], v[92:95]
	v_mfma_f32_16x16x32_bf16 v[88:91], v[136:139], v[188:191], v[88:91]
	v_mfma_f32_16x16x32_bf16 v[76:79], v[128:131], v[196:199], v[76:79]
	v_mfma_f32_16x16x32_bf16 v[72:75], v[136:139], v[196:199], v[72:75]
	v_mfma_f32_16x16x32_bf16 v[124:127], v[132:135], v[168:171], v[124:127]
	v_mfma_f32_16x16x32_bf16 v[120:123], v[140:143], v[168:171], v[120:123]
	v_mfma_f32_16x16x32_bf16 v[108:111], v[132:135], v[184:187], v[108:111]
	v_mfma_f32_16x16x32_bf16 v[104:107], v[140:143], v[184:187], v[104:107]
	v_mfma_f32_16x16x32_bf16 v[92:95], v[132:135], v[192:195], v[92:95]
	v_mfma_f32_16x16x32_bf16 v[88:91], v[140:143], v[192:195], v[88:91]
	v_mfma_f32_16x16x32_bf16 v[76:79], v[132:135], v[200:203], v[76:79]
	v_mfma_f32_16x16x32_bf16 v[72:75], v[140:143], v[200:203], v[72:75]
	s_setprio 1
	s_barrier
	s_add_i32 s39, s80, s33
	v_lshl_add_u64 v[176:177], s[6:7], 0, v[150:151]
	s_mov_b32 m0, s39
	ds_read_b128 v[204:207], v183
	ds_read_b128 v[210:213], v183 offset:1024
	ds_read_b128 v[214:217], v183 offset:2048
	ds_read_b128 v[218:221], v183 offset:3072
	global_load_lds_dwordx4 v[176:177], off
	v_lshl_add_u64 v[222:223], s[6:7], 0, v[154:155]
	s_add_i32 m0, s39, 0x2000
	s_nop 0
	global_load_lds_dwordx4 v[222:223], off
	s_barrier
	s_waitcnt lgkmcnt(0)
	s_setprio 0
	s_waitcnt lgkmcnt(0)
	v_mfma_f32_16x16x32_bf16 v[116:119], v[204:207], v[144:147], v[116:119]
	v_mfma_f32_16x16x32_bf16 v[112:115], v[214:217], v[144:147], v[112:115]
	v_mfma_f32_16x16x32_bf16 v[100:103], v[204:207], v[172:175], v[100:103]
	v_mfma_f32_16x16x32_bf16 v[96:99], v[214:217], v[172:175], v[96:99]
	v_mfma_f32_16x16x32_bf16 v[84:87], v[204:207], v[188:191], v[84:87]
	v_mfma_f32_16x16x32_bf16 v[80:83], v[214:217], v[188:191], v[80:83]
	v_mfma_f32_16x16x32_bf16 v[68:71], v[204:207], v[196:199], v[68:71]
	v_mfma_f32_16x16x32_bf16 v[64:67], v[214:217], v[196:199], v[64:67]
	v_mfma_f32_16x16x32_bf16 v[116:119], v[210:213], v[168:171], v[116:119]
	v_mfma_f32_16x16x32_bf16 v[112:115], v[218:221], v[168:171], v[112:115]
	v_mfma_f32_16x16x32_bf16 v[100:103], v[210:213], v[184:187], v[100:103]
	v_mfma_f32_16x16x32_bf16 v[96:99], v[218:221], v[184:187], v[96:99]
	v_mfma_f32_16x16x32_bf16 v[84:87], v[210:213], v[192:195], v[84:87]
	v_mfma_f32_16x16x32_bf16 v[80:83], v[218:221], v[192:195], v[80:83]
	v_mfma_f32_16x16x32_bf16 v[68:71], v[210:213], v[200:203], v[68:71]
	v_mfma_f32_16x16x32_bf16 v[64:67], v[218:221], v[200:203], v[64:67]
	s_setprio 1
	s_mov_b32 m0, s44
	v_lshl_add_u64 v[224:225], s[8:9], 0, v[148:149]
	s_barrier
	ds_read_b128 v[144:147], v182 offset:16384
	ds_read_b128 v[168:171], v182 offset:17408
	ds_read_b128 v[172:175], v182 offset:18432
	ds_read_b128 v[184:187], v182 offset:19456
	ds_read_b128 v[188:191], v182 offset:20480
	ds_read_b128 v[192:195], v182 offset:21504
	ds_read_b128 v[196:199], v182 offset:22528
	ds_read_b128 v[200:203], v182 offset:23552
	global_load_lds_dwordx4 v[224:225], off
	v_lshl_add_u64 v[226:227], s[8:9], 0, v[152:153]
	s_mov_b32 m0, s45
	s_nop 0
	global_load_lds_dwordx4 v[226:227], off
	s_barrier
	s_waitcnt lgkmcnt(0)
	s_setprio 0
	s_waitcnt lgkmcnt(0)
	v_mfma_f32_16x16x32_bf16 v[60:63], v[128:131], v[144:147], v[60:63]
	v_mfma_f32_16x16x32_bf16 v[56:59], v[136:139], v[144:147], v[56:59]
	v_mfma_f32_16x16x32_bf16 v[44:47], v[128:131], v[172:175], v[44:47]
	v_mfma_f32_16x16x32_bf16 v[40:43], v[136:139], v[172:175], v[40:43]
	v_mfma_f32_16x16x32_bf16 v[28:31], v[128:131], v[188:191], v[28:31]
	v_mfma_f32_16x16x32_bf16 v[24:27], v[136:139], v[188:191], v[24:27]
	v_mfma_f32_16x16x32_bf16 v[12:15], v[128:131], v[196:199], v[12:15]
	v_mfma_f32_16x16x32_bf16 v[8:11], v[136:139], v[196:199], v[8:11]
	v_mfma_f32_16x16x32_bf16 v[60:63], v[132:135], v[168:171], v[60:63]
	v_mfma_f32_16x16x32_bf16 v[56:59], v[140:143], v[168:171], v[56:59]
	v_mfma_f32_16x16x32_bf16 v[44:47], v[132:135], v[184:187], v[44:47]
	v_mfma_f32_16x16x32_bf16 v[40:43], v[140:143], v[184:187], v[40:43]
	v_mfma_f32_16x16x32_bf16 v[28:31], v[132:135], v[192:195], v[28:31]
	v_mfma_f32_16x16x32_bf16 v[24:27], v[140:143], v[192:195], v[24:27]
	v_mfma_f32_16x16x32_bf16 v[12:15], v[132:135], v[200:203], v[12:15]
	v_mfma_f32_16x16x32_bf16 v[8:11], v[140:143], v[200:203], v[8:11]
	s_setprio 1
	s_barrier
	s_add_u32 s78, s6, 0x80000
	s_addc_u32 s79, s7, 0
	s_add_i32 s39, s81, s33
	v_lshl_add_u64 v[128:129], s[78:79], 0, v[150:151]
	s_mov_b32 m0, s39
	s_nop 0
	global_load_lds_dwordx4 v[128:129], off
	v_lshl_add_u64 v[128:129], s[78:79], 0, v[154:155]
	s_add_i32 m0, s39, 0x2000
	s_nop 0
	global_load_lds_dwordx4 v[128:129], off
	s_waitcnt vmcnt(6)
	s_barrier
	s_setprio 0
	v_mfma_f32_16x16x32_bf16 v[52:55], v[204:207], v[144:147], v[52:55]
	v_mfma_f32_16x16x32_bf16 v[48:51], v[214:217], v[144:147], v[48:51]
	v_mfma_f32_16x16x32_bf16 v[36:39], v[204:207], v[172:175], v[36:39]
	v_mfma_f32_16x16x32_bf16 v[32:35], v[214:217], v[172:175], v[32:35]
	v_mfma_f32_16x16x32_bf16 v[20:23], v[204:207], v[188:191], v[20:23]
	v_mfma_f32_16x16x32_bf16 v[16:19], v[214:217], v[188:191], v[16:19]
	v_mfma_f32_16x16x32_bf16 v[4:7], v[204:207], v[196:199], v[4:7]
	v_mfma_f32_16x16x32_bf16 v[0:3], v[214:217], v[196:199], v[0:3]
	v_mfma_f32_16x16x32_bf16 v[52:55], v[210:213], v[168:171], v[52:55]
	v_mfma_f32_16x16x32_bf16 v[48:51], v[218:221], v[168:171], v[48:51]
	v_mfma_f32_16x16x32_bf16 v[36:39], v[210:213], v[184:187], v[36:39]
	v_mfma_f32_16x16x32_bf16 v[32:35], v[218:221], v[184:187], v[32:35]
	v_mfma_f32_16x16x32_bf16 v[20:23], v[210:213], v[192:195], v[20:23]
	v_mfma_f32_16x16x32_bf16 v[16:19], v[218:221], v[192:195], v[16:19]
	v_mfma_f32_16x16x32_bf16 v[4:7], v[210:213], v[200:203], v[4:7]
	v_mfma_f32_16x16x32_bf16 v[0:3], v[218:221], v[200:203], v[0:3]
	s_setprio 1
	s_add_i32 s39, 0, 0x18000
	v_add_u32_e32 v140, s39, v180
	s_barrier
	ds_read_b128 v[128:131], v140
	ds_read_b128 v[132:135], v140 offset:1024
	ds_read_b128 v[136:139], v140 offset:2048
	ds_read_b128 v[140:143], v140 offset:3072
	s_add_u32 s8, s8, 0x80000
	s_addc_u32 s9, s9, 0
	s_mov_b32 m0, s51
	v_lshl_add_u64 v[204:205], s[8:9], 0, v[148:149]
	ds_read_b128 v[144:147], v182 offset:32768
	ds_read_b128 v[168:171], v182 offset:33792
	ds_read_b128 v[172:175], v182 offset:34816
	ds_read_b128 v[184:187], v182 offset:35840
	ds_read_b128 v[188:191], v182 offset:36864
	ds_read_b128 v[192:195], v182 offset:37888
	ds_read_b128 v[196:199], v182 offset:38912
	ds_read_b128 v[200:203], v182 offset:39936
	global_load_lds_dwordx4 v[204:205], off
	v_lshl_add_u64 v[204:205], s[8:9], 0, v[152:153]
	s_mov_b32 m0, s55
	s_nop 0
	global_load_lds_dwordx4 v[204:205], off
	s_waitcnt lgkmcnt(8)
	s_barrier
	s_waitcnt lgkmcnt(0)
	s_setprio 0
	s_waitcnt lgkmcnt(0)
	v_mfma_f32_16x16x32_bf16 v[124:127], v[128:131], v[144:147], v[124:127]
	v_mfma_f32_16x16x32_bf16 v[120:123], v[136:139], v[144:147], v[120:123]
	v_mfma_f32_16x16x32_bf16 v[108:111], v[128:131], v[172:175], v[108:111]
	v_mfma_f32_16x16x32_bf16 v[104:107], v[136:139], v[172:175], v[104:107]
	v_mfma_f32_16x16x32_bf16 v[92:95], v[128:131], v[188:191], v[92:95]
	v_mfma_f32_16x16x32_bf16 v[88:91], v[136:139], v[188:191], v[88:91]
	v_mfma_f32_16x16x32_bf16 v[76:79], v[128:131], v[196:199], v[76:79]
	v_mfma_f32_16x16x32_bf16 v[72:75], v[136:139], v[196:199], v[72:75]
	v_mfma_f32_16x16x32_bf16 v[124:127], v[132:135], v[168:171], v[124:127]
	v_mfma_f32_16x16x32_bf16 v[120:123], v[140:143], v[168:171], v[120:123]
	v_mfma_f32_16x16x32_bf16 v[108:111], v[132:135], v[184:187], v[108:111]
	v_mfma_f32_16x16x32_bf16 v[104:107], v[140:143], v[184:187], v[104:107]
	v_mfma_f32_16x16x32_bf16 v[92:95], v[132:135], v[192:195], v[92:95]
	v_mfma_f32_16x16x32_bf16 v[88:91], v[140:143], v[192:195], v[88:91]
	v_mfma_f32_16x16x32_bf16 v[76:79], v[132:135], v[200:203], v[76:79]
	v_mfma_f32_16x16x32_bf16 v[72:75], v[140:143], v[200:203], v[72:75]
	s_setprio 1
	s_barrier
	s_add_i32 s8, 0, 0x1c000
	s_add_i32 s9, s39, s33
	v_add_u32_e32 v156, s8, v180
	v_lshl_add_u64 v[176:177], v[176:177], 0, s[24:25]
	s_mov_b32 m0, s9
	ds_read_b128 v[204:207], v156
	ds_read_b128 v[210:213], v156 offset:1024
	ds_read_b128 v[214:217], v156 offset:2048
	ds_read_b128 v[218:221], v156 offset:3072
	global_load_lds_dwordx4 v[176:177], off
	v_lshl_add_u64 v[176:177], v[222:223], 0, s[24:25]
	s_add_i32 m0, s9, 0x2000
	s_nop 0
	global_load_lds_dwordx4 v[176:177], off
	s_barrier
	s_waitcnt lgkmcnt(0)
	s_setprio 0
	s_waitcnt lgkmcnt(0)
	v_mfma_f32_16x16x32_bf16 v[116:119], v[204:207], v[144:147], v[116:119]
	v_mfma_f32_16x16x32_bf16 v[112:115], v[214:217], v[144:147], v[112:115]
	v_mfma_f32_16x16x32_bf16 v[100:103], v[204:207], v[172:175], v[100:103]
	v_mfma_f32_16x16x32_bf16 v[96:99], v[214:217], v[172:175], v[96:99]
	v_mfma_f32_16x16x32_bf16 v[84:87], v[204:207], v[188:191], v[84:87]
	v_mfma_f32_16x16x32_bf16 v[80:83], v[214:217], v[188:191], v[80:83]
	v_mfma_f32_16x16x32_bf16 v[68:71], v[204:207], v[196:199], v[68:71]
	v_mfma_f32_16x16x32_bf16 v[64:67], v[214:217], v[196:199], v[64:67]
	v_mfma_f32_16x16x32_bf16 v[116:119], v[210:213], v[168:171], v[116:119]
	v_mfma_f32_16x16x32_bf16 v[112:115], v[218:221], v[168:171], v[112:115]
	v_mfma_f32_16x16x32_bf16 v[100:103], v[210:213], v[184:187], v[100:103]
	v_mfma_f32_16x16x32_bf16 v[96:99], v[218:221], v[184:187], v[96:99]
	v_mfma_f32_16x16x32_bf16 v[84:87], v[210:213], v[192:195], v[84:87]
	v_mfma_f32_16x16x32_bf16 v[80:83], v[218:221], v[192:195], v[80:83]
	v_mfma_f32_16x16x32_bf16 v[68:71], v[210:213], v[200:203], v[68:71]
	v_mfma_f32_16x16x32_bf16 v[64:67], v[218:221], v[200:203], v[64:67]
	s_setprio 1
	s_mov_b32 m0, s83
	v_lshl_add_u64 v[176:177], v[224:225], 0, s[24:25]
	s_barrier
	ds_read_b128 v[144:147], v182 offset:49152
	ds_read_b128 v[168:171], v182 offset:50176
	ds_read_b128 v[172:175], v182 offset:51200
	ds_read_b128 v[184:187], v182 offset:52224
	ds_read_b128 v[188:191], v182 offset:53248
	ds_read_b128 v[192:195], v182 offset:54272
	ds_read_b128 v[196:199], v182 offset:55296
	ds_read_b128 v[200:203], v182 offset:56320
	global_load_lds_dwordx4 v[176:177], off
	v_lshl_add_u64 v[176:177], v[226:227], 0, s[24:25]
	s_mov_b32 m0, s91
	s_nop 0
	global_load_lds_dwordx4 v[176:177], off
	s_barrier
	s_waitcnt lgkmcnt(0)
	s_setprio 0
	s_waitcnt lgkmcnt(0)
	v_mfma_f32_16x16x32_bf16 v[60:63], v[128:131], v[144:147], v[60:63]
	v_mfma_f32_16x16x32_bf16 v[56:59], v[136:139], v[144:147], v[56:59]
	v_mfma_f32_16x16x32_bf16 v[44:47], v[128:131], v[172:175], v[44:47]
	v_mfma_f32_16x16x32_bf16 v[40:43], v[136:139], v[172:175], v[40:43]
	v_mfma_f32_16x16x32_bf16 v[28:31], v[128:131], v[188:191], v[28:31]
	v_mfma_f32_16x16x32_bf16 v[24:27], v[136:139], v[188:191], v[24:27]
	v_mfma_f32_16x16x32_bf16 v[12:15], v[128:131], v[196:199], v[12:15]
	v_mfma_f32_16x16x32_bf16 v[8:11], v[136:139], v[196:199], v[8:11]
	v_mfma_f32_16x16x32_bf16 v[60:63], v[132:135], v[168:171], v[60:63]
	v_mfma_f32_16x16x32_bf16 v[56:59], v[140:143], v[168:171], v[56:59]
	v_mfma_f32_16x16x32_bf16 v[44:47], v[132:135], v[184:187], v[44:47]
	v_mfma_f32_16x16x32_bf16 v[40:43], v[140:143], v[184:187], v[40:43]
	v_mfma_f32_16x16x32_bf16 v[28:31], v[132:135], v[192:195], v[28:31]
	v_mfma_f32_16x16x32_bf16 v[24:27], v[140:143], v[192:195], v[24:27]
	v_mfma_f32_16x16x32_bf16 v[12:15], v[132:135], v[200:203], v[12:15]
	v_mfma_f32_16x16x32_bf16 v[8:11], v[140:143], v[200:203], v[8:11]
	s_setprio 1
	s_barrier
	s_add_u32 s6, s6, 0x80080
	s_addc_u32 s7, s7, 0
	s_add_i32 s8, s8, s33
	v_lshl_add_u64 v[128:129], s[6:7], 0, v[150:151]
	s_mov_b32 m0, s8
	s_nop 0
	global_load_lds_dwordx4 v[128:129], off
	v_lshl_add_u64 v[128:129], s[6:7], 0, v[154:155]
	s_add_i32 m0, s8, 0x2000
	s_nop 0
	global_load_lds_dwordx4 v[128:129], off
	s_waitcnt vmcnt(6)
	s_barrier
	s_setprio 0
	v_mfma_f32_16x16x32_bf16 v[52:55], v[204:207], v[144:147], v[52:55]
	v_mfma_f32_16x16x32_bf16 v[48:51], v[214:217], v[144:147], v[48:51]
	v_mfma_f32_16x16x32_bf16 v[36:39], v[204:207], v[172:175], v[36:39]
	v_mfma_f32_16x16x32_bf16 v[32:35], v[214:217], v[172:175], v[32:35]
	v_mfma_f32_16x16x32_bf16 v[20:23], v[204:207], v[188:191], v[20:23]
	v_mfma_f32_16x16x32_bf16 v[16:19], v[214:217], v[188:191], v[16:19]
	v_mfma_f32_16x16x32_bf16 v[4:7], v[204:207], v[196:199], v[4:7]
	v_mfma_f32_16x16x32_bf16 v[0:3], v[214:217], v[196:199], v[0:3]
	v_mfma_f32_16x16x32_bf16 v[52:55], v[210:213], v[168:171], v[52:55]
	v_mfma_f32_16x16x32_bf16 v[48:51], v[218:221], v[168:171], v[48:51]
	v_mfma_f32_16x16x32_bf16 v[36:39], v[210:213], v[184:187], v[36:39]
	v_mfma_f32_16x16x32_bf16 v[32:35], v[218:221], v[184:187], v[32:35]
	v_mfma_f32_16x16x32_bf16 v[20:23], v[210:213], v[192:195], v[20:23]
	v_mfma_f32_16x16x32_bf16 v[16:19], v[218:221], v[192:195], v[16:19]
	v_mfma_f32_16x16x32_bf16 v[4:7], v[210:213], v[200:203], v[4:7]
	v_mfma_f32_16x16x32_bf16 v[0:3], v[218:221], v[200:203], v[0:3]
	s_setprio 1
	s_add_i32 s37, s37, 2
	s_add_u32 s4, s4, 0x100
	s_addc_u32 s5, s5, 0
	s_add_u32 s35, s35, 0x100
	s_addc_u32 s36, s36, 0
	s_cmp_gt_u32 s37, 29
	s_barrier
	s_cbranch_scc0 .LBB0_262
	v_mov_b32_e32 v185, v179
	v_mov_b32_e32 v184, v178
	s_cmp_lt_i32 s90, 33
	s_mov_b64 s[4:5], -1
	s_cbranch_scc0 .LBB0_589
	s_cmp_gt_i32 s82, 3
	s_cbranch_scc0 .LBB0_586
	s_cmp_gt_u32 s82, 7
	s_cbranch_scc0 .LBB0_551
	s_cmp_gt_u32 s82, 15
	s_cbranch_scc0 .LBB0_548
	s_cmp_gt_u32 s82, 23
	s_cbranch_scc0 .LBB0_545
	s_cmp_gt_u32 s82, 27
	s_cbranch_scc0 .LBB0_486
	s_cmp_gt_u32 s82, 31
	s_cbranch_scc0 .LBB0_315
	s_cmp_gt_u32 s82, 35
	s_cbranch_scc0 .LBB0_280
	s_cmp_gt_u32 s82, 39
	s_cbranch_scc0 .LBB0_277
	s_lshl_b32 s4, s90, 8
	s_add_i32 s4, s4, s57
	v_lshl_add_u32 v128, v185, 3, s59
	v_add_u32_e32 v132, s4, v184
	v_ashrrev_i32_e32 v129, 31, v128
	v_mad_i64_i32 v[130:131], s[4:5], v132, s28, 0
	s_cmp_gt_u32 s82, 41
	s_mov_b64 s[4:5], -1
	v_lshl_add_u64 v[130:131], s[0:1], 0, v[130:131]
	v_lshlrev_b64 v[128:129], 1, v[128:129]
	v_add_u32_e32 v138, 16, v132
	v_add_u32_e32 v137, 32, v132
	v_add_u32_e32 v136, 48, v132
	v_add_u32_e32 v135, 0x80, v132
	v_add_u32_e32 v134, 0x90, v132
	v_add_u32_e32 v133, 0xa0, v132
	v_add_u32_e32 v132, 0xb0, v132
	s_cbranch_scc0 .LBB0_274
	s_lshl_b32 s20, s82, 8
	s_lshl_b64 s[4:5], s[20:21], 1
	v_lshl_add_u64 v[144:145], v[130:131], 0, s[4:5]
	v_cvt_pk_bf16_f32 v140, v124, v125
	v_cvt_pk_bf16_f32 v141, v126, v127
	v_cvt_pk_bf16_f32 v142, v120, v121
	v_cvt_pk_bf16_f32 v143, v122, v123
	v_lshl_add_u64 v[144:145], v[144:145], 0, v[128:129]
	global_store_dwordx4 v[144:145], v[140:143], off
	s_nop 1
	v_cvt_pk_bf16_f32 v140, v116, v117
	v_cvt_pk_bf16_f32 v141, v118, v119
	v_cvt_pk_bf16_f32 v142, v112, v113
	v_cvt_pk_bf16_f32 v143, v114, v115
	global_store_dwordx4 v[144:145], v[140:143], off offset:256
	v_mov_b64_e32 v[144:145], s[0:1]
	v_mad_i64_i32 v[146:147], s[6:7], v138, s28, v[144:145]
	v_lshl_add_u64 v[146:147], v[146:147], 0, s[4:5]
	v_cvt_pk_bf16_f32 v140, v108, v109
	v_cvt_pk_bf16_f32 v141, v110, v111
	v_cvt_pk_bf16_f32 v142, v104, v105
	v_cvt_pk_bf16_f32 v143, v106, v107
	v_lshl_add_u64 v[146:147], v[146:147], 0, v[128:129]
	global_store_dwordx4 v[146:147], v[140:143], off
	s_nop 1
	v_cvt_pk_bf16_f32 v140, v100, v101
	v_cvt_pk_bf16_f32 v141, v102, v103
	v_cvt_pk_bf16_f32 v142, v96, v97
	v_cvt_pk_bf16_f32 v143, v98, v99
	global_store_dwordx4 v[146:147], v[140:143], off offset:256
	v_mad_i64_i32 v[146:147], s[6:7], v137, s28, v[144:145]
	v_lshl_add_u64 v[146:147], v[146:147], 0, s[4:5]
	v_cvt_pk_bf16_f32 v140, v92, v93
	v_cvt_pk_bf16_f32 v141, v94, v95
	v_cvt_pk_bf16_f32 v142, v88, v89
	v_cvt_pk_bf16_f32 v143, v90, v91
	v_lshl_add_u64 v[146:147], v[146:147], 0, v[128:129]
	global_store_dwordx4 v[146:147], v[140:143], off
	s_nop 1
	v_cvt_pk_bf16_f32 v140, v84, v85
	v_cvt_pk_bf16_f32 v141, v86, v87
	v_cvt_pk_bf16_f32 v142, v80, v81
	v_cvt_pk_bf16_f32 v143, v82, v83
	global_store_dwordx4 v[146:147], v[140:143], off offset:256
	v_mad_i64_i32 v[146:147], s[6:7], v136, s28, v[144:145]
	v_lshl_add_u64 v[146:147], v[146:147], 0, s[4:5]
	v_cvt_pk_bf16_f32 v140, v76, v77
	v_cvt_pk_bf16_f32 v141, v78, v79
	v_cvt_pk_bf16_f32 v142, v72, v73
	v_cvt_pk_bf16_f32 v143, v74, v75
	v_lshl_add_u64 v[146:147], v[146:147], 0, v[128:129]
	global_store_dwordx4 v[146:147], v[140:143], off
	s_nop 1
	v_cvt_pk_bf16_f32 v140, v68, v69
	v_cvt_pk_bf16_f32 v141, v70, v71
	v_cvt_pk_bf16_f32 v142, v64, v65
	v_cvt_pk_bf16_f32 v143, v66, v67
	global_store_dwordx4 v[146:147], v[140:143], off offset:256
	v_mad_i64_i32 v[146:147], s[6:7], v135, s28, v[144:145]
	v_lshl_add_u64 v[146:147], v[146:147], 0, s[4:5]
	v_cvt_pk_bf16_f32 v140, v60, v61
	v_cvt_pk_bf16_f32 v141, v62, v63
	v_cvt_pk_bf16_f32 v142, v56, v57
	v_cvt_pk_bf16_f32 v143, v58, v59
	v_lshl_add_u64 v[146:147], v[146:147], 0, v[128:129]
	global_store_dwordx4 v[146:147], v[140:143], off
	s_nop 1
	v_cvt_pk_bf16_f32 v140, v52, v53
	v_cvt_pk_bf16_f32 v141, v54, v55
	v_cvt_pk_bf16_f32 v142, v48, v49
	v_cvt_pk_bf16_f32 v143, v50, v51
	global_store_dwordx4 v[146:147], v[140:143], off offset:256
	v_mad_i64_i32 v[146:147], s[6:7], v134, s28, v[144:145]
	v_lshl_add_u64 v[146:147], v[146:147], 0, s[4:5]
	v_cvt_pk_bf16_f32 v140, v44, v45
	v_cvt_pk_bf16_f32 v141, v46, v47
	v_cvt_pk_bf16_f32 v142, v40, v41
	v_cvt_pk_bf16_f32 v143, v42, v43
	v_lshl_add_u64 v[146:147], v[146:147], 0, v[128:129]
	global_store_dwordx4 v[146:147], v[140:143], off
	s_nop 1
	v_cvt_pk_bf16_f32 v140, v36, v37
	v_cvt_pk_bf16_f32 v141, v38, v39
	v_cvt_pk_bf16_f32 v142, v32, v33
	v_cvt_pk_bf16_f32 v143, v34, v35
	global_store_dwordx4 v[146:147], v[140:143], off offset:256
	v_mad_i64_i32 v[146:147], s[6:7], v133, s28, v[144:145]
	v_lshl_add_u64 v[146:147], v[146:147], 0, s[4:5]
	v_cvt_pk_bf16_f32 v140, v28, v29
	v_cvt_pk_bf16_f32 v141, v30, v31
	v_cvt_pk_bf16_f32 v142, v24, v25
	v_cvt_pk_bf16_f32 v143, v26, v27
	v_lshl_add_u64 v[146:147], v[146:147], 0, v[128:129]
	v_mad_i64_i32 v[144:145], s[6:7], v132, s28, v[144:145]
	global_store_dwordx4 v[146:147], v[140:143], off
	v_lshl_add_u64 v[144:145], v[144:145], 0, s[4:5]
	v_lshl_add_u64 v[144:145], v[144:145], 0, v[128:129]
	v_cvt_pk_bf16_f32 v140, v20, v21
	v_cvt_pk_bf16_f32 v141, v22, v23
	v_cvt_pk_bf16_f32 v142, v16, v17
	v_cvt_pk_bf16_f32 v143, v18, v19
	global_store_dwordx4 v[146:147], v[140:143], off offset:256
	s_mov_b64 s[4:5], 0
	s_nop 0
	v_cvt_pk_bf16_f32 v140, v12, v13
	v_cvt_pk_bf16_f32 v141, v14, v15
	v_cvt_pk_bf16_f32 v142, v8, v9
	v_cvt_pk_bf16_f32 v143, v10, v11
	global_store_dwordx4 v[144:145], v[140:143], off
	s_nop 1
	v_cvt_pk_bf16_f32 v140, v4, v5
	v_cvt_pk_bf16_f32 v141, v6, v7
	v_cvt_pk_bf16_f32 v142, v0, v1
	v_cvt_pk_bf16_f32 v143, v2, v3
	global_store_dwordx4 v[144:145], v[140:143], off offset:256

.LBB0_974:
	ds_read_b128 v[150:153], v147
	ds_read_b128 v[154:157], v147 offset:1024
	ds_read_b128 v[158:161], v147 offset:2048
	ds_read_b128 v[162:165], v147 offset:3072
	s_add_u32 s16, s14, 0x100
	s_addc_u32 s17, s15, 0
	s_cmp_eq_u32 s44, 52
	s_cselect_b32 s21, s3, s17
	s_cselect_b32 s20, s2, s16
	s_cselect_b32 s19, s5, s43
	s_cselect_b32 s18, s4, s42
	v_lshl_add_u64 v[198:199], s[14:15], 0, v[136:137]
	s_add_i32 m0, s24, 0xc000
	ds_read_b128 v[166:169], v148
	ds_read_b128 v[170:173], v148 offset:1024
	ds_read_b128 v[174:177], v148 offset:2048
	ds_read_b128 v[178:181], v148 offset:3072
	ds_read_b128 v[182:185], v148 offset:4096
	ds_read_b128 v[186:189], v148 offset:5120
	ds_read_b128 v[190:193], v148 offset:6144
	ds_read_b128 v[194:197], v148 offset:7168
	global_load_lds_dwordx4 v[198:199], off
	v_lshl_add_u64 v[198:199], s[14:15], 0, v[138:139]
	s_add_i32 m0, s24, 0xe000
	s_nop 0
	global_load_lds_dwordx4 v[198:199], off
	s_waitcnt lgkmcnt(8)
	s_barrier
	s_waitcnt lgkmcnt(0)
	s_setprio 0
	s_waitcnt lgkmcnt(0)
	v_mfma_f32_16x16x32_bf16 v[124:127], v[150:153], v[166:169], v[124:127]
	v_mfma_f32_16x16x32_bf16 v[120:123], v[158:161], v[166:169], v[120:123]
	v_mfma_f32_16x16x32_bf16 v[116:119], v[150:153], v[174:177], v[116:119]
	v_mfma_f32_16x16x32_bf16 v[112:115], v[158:161], v[174:177], v[112:115]
	v_mfma_f32_16x16x32_bf16 v[100:103], v[150:153], v[182:185], v[100:103]
	v_mfma_f32_16x16x32_bf16 v[96:99], v[158:161], v[182:185], v[96:99]
	v_mfma_f32_16x16x32_bf16 v[84:87], v[150:153], v[190:193], v[84:87]
	v_mfma_f32_16x16x32_bf16 v[80:83], v[158:161], v[190:193], v[80:83]
	v_mfma_f32_16x16x32_bf16 v[124:127], v[154:157], v[170:173], v[124:127]
	v_mfma_f32_16x16x32_bf16 v[120:123], v[162:165], v[170:173], v[120:123]
	v_mfma_f32_16x16x32_bf16 v[116:119], v[154:157], v[178:181], v[116:119]
	v_mfma_f32_16x16x32_bf16 v[112:115], v[162:165], v[178:181], v[112:115]
	v_mfma_f32_16x16x32_bf16 v[100:103], v[154:157], v[186:189], v[100:103]
	v_mfma_f32_16x16x32_bf16 v[96:99], v[162:165], v[186:189], v[96:99]
	v_mfma_f32_16x16x32_bf16 v[84:87], v[154:157], v[194:197], v[84:87]
	v_mfma_f32_16x16x32_bf16 v[80:83], v[162:165], v[194:197], v[80:83]
	s_setprio 1
	s_barrier
	s_add_i32 s14, s35, s23
	v_lshl_add_u64 v[206:207], s[18:19], 0, v[130:131]
	s_mov_b32 m0, s14
	ds_read_b128 v[198:201], v149
	ds_read_b128 v[202:205], v149 offset:1024
	ds_read_b128 v[210:213], v149 offset:2048
	ds_read_b128 v[214:217], v149 offset:3072
	global_load_lds_dwordx4 v[206:207], off
	v_lshl_add_u64 v[218:219], s[18:19], 0, v[134:135]
	s_add_i32 m0, s14, 0x2000
	s_nop 0
	global_load_lds_dwordx4 v[218:219], off
	s_barrier
	s_waitcnt lgkmcnt(0)
	s_setprio 0
	s_waitcnt lgkmcnt(0)
	v_mfma_f32_16x16x32_bf16 v[108:111], v[198:201], v[166:169], v[108:111]
	v_mfma_f32_16x16x32_bf16 v[104:107], v[210:213], v[166:169], v[104:107]
	v_mfma_f32_16x16x32_bf16 v[92:95], v[198:201], v[174:177], v[92:95]
	v_mfma_f32_16x16x32_bf16 v[88:91], v[210:213], v[174:177], v[88:91]
	v_mfma_f32_16x16x32_bf16 v[76:79], v[198:201], v[182:185], v[76:79]
	v_mfma_f32_16x16x32_bf16 v[72:75], v[210:213], v[182:185], v[72:75]
	v_mfma_f32_16x16x32_bf16 v[68:71], v[198:201], v[190:193], v[68:71]
	v_mfma_f32_16x16x32_bf16 v[64:67], v[210:213], v[190:193], v[64:67]
	v_mfma_f32_16x16x32_bf16 v[108:111], v[202:205], v[170:173], v[108:111]
	v_mfma_f32_16x16x32_bf16 v[104:107], v[214:217], v[170:173], v[104:107]
	v_mfma_f32_16x16x32_bf16 v[92:95], v[202:205], v[178:181], v[92:95]
	v_mfma_f32_16x16x32_bf16 v[88:91], v[214:217], v[178:181], v[88:91]
	v_mfma_f32_16x16x32_bf16 v[76:79], v[202:205], v[186:189], v[76:79]
	v_mfma_f32_16x16x32_bf16 v[72:75], v[214:217], v[186:189], v[72:75]
	v_mfma_f32_16x16x32_bf16 v[68:71], v[202:205], v[194:197], v[68:71]
	v_mfma_f32_16x16x32_bf16 v[64:67], v[214:217], v[194:197], v[64:67]
	s_setprio 1
	s_mov_b32 m0, s24
	v_lshl_add_u64 v[220:221], s[20:21], 0, v[128:129]
	s_barrier
	ds_read_b128 v[166:169], v148 offset:16384
	ds_read_b128 v[170:173], v148 offset:17408
	ds_read_b128 v[174:177], v148 offset:18432
	ds_read_b128 v[178:181], v148 offset:19456
	ds_read_b128 v[182:185], v148 offset:20480
	ds_read_b128 v[186:189], v148 offset:21504
	ds_read_b128 v[190:193], v148 offset:22528
	ds_read_b128 v[194:197], v148 offset:23552
	global_load_lds_dwordx4 v[220:221], off
	v_lshl_add_u64 v[222:223], s[20:21], 0, v[132:133]
	s_mov_b32 m0, s25
	s_nop 0
	global_load_lds_dwordx4 v[222:223], off
	s_barrier
	s_waitcnt lgkmcnt(0)
	s_setprio 0
	s_waitcnt lgkmcnt(0)
	v_mfma_f32_16x16x32_bf16 v[60:63], v[150:153], v[166:169], v[60:63]
	v_mfma_f32_16x16x32_bf16 v[56:59], v[158:161], v[166:169], v[56:59]
	v_mfma_f32_16x16x32_bf16 v[52:55], v[150:153], v[174:177], v[52:55]
	v_mfma_f32_16x16x32_bf16 v[48:51], v[158:161], v[174:177], v[48:51]
	v_mfma_f32_16x16x32_bf16 v[36:39], v[150:153], v[182:185], v[36:39]
	v_mfma_f32_16x16x32_bf16 v[32:35], v[158:161], v[182:185], v[32:35]
	v_mfma_f32_16x16x32_bf16 v[20:23], v[150:153], v[190:193], v[20:23]
	v_mfma_f32_16x16x32_bf16 v[16:19], v[158:161], v[190:193], v[16:19]
	v_mfma_f32_16x16x32_bf16 v[60:63], v[154:157], v[170:173], v[60:63]
	v_mfma_f32_16x16x32_bf16 v[56:59], v[162:165], v[170:173], v[56:59]
	v_mfma_f32_16x16x32_bf16 v[52:55], v[154:157], v[178:181], v[52:55]
	v_mfma_f32_16x16x32_bf16 v[48:51], v[162:165], v[178:181], v[48:51]
	v_mfma_f32_16x16x32_bf16 v[36:39], v[154:157], v[186:189], v[36:39]
	v_mfma_f32_16x16x32_bf16 v[32:35], v[162:165], v[186:189], v[32:35]
	v_mfma_f32_16x16x32_bf16 v[20:23], v[154:157], v[194:197], v[20:23]
	v_mfma_f32_16x16x32_bf16 v[16:19], v[162:165], v[194:197], v[16:19]
	s_setprio 1
	s_barrier
	s_add_u32 s14, s18, 0xe0000
	s_addc_u32 s15, s19, 0
	s_add_i32 s45, s36, s23
	v_lshl_add_u64 v[150:151], s[14:15], 0, v[130:131]
	s_mov_b32 m0, s45
	s_nop 0
	global_load_lds_dwordx4 v[150:151], off
	v_lshl_add_u64 v[150:151], s[14:15], 0, v[134:135]
	s_add_i32 m0, s45, 0x2000
	s_nop 0
	global_load_lds_dwordx4 v[150:151], off
	s_waitcnt vmcnt(6)
	s_barrier
	s_setprio 0
	v_mfma_f32_16x16x32_bf16 v[44:47], v[198:201], v[166:169], v[44:47]
	v_mfma_f32_16x16x32_bf16 v[40:43], v[210:213], v[166:169], v[40:43]
	v_mfma_f32_16x16x32_bf16 v[28:31], v[198:201], v[174:177], v[28:31]
	v_mfma_f32_16x16x32_bf16 v[24:27], v[210:213], v[174:177], v[24:27]
	v_mfma_f32_16x16x32_bf16 v[12:15], v[198:201], v[182:185], v[12:15]
	v_mfma_f32_16x16x32_bf16 v[8:11], v[210:213], v[182:185], v[8:11]
	v_mfma_f32_16x16x32_bf16 v[4:7], v[198:201], v[190:193], v[4:7]
	v_mfma_f32_16x16x32_bf16 v[0:3], v[210:213], v[190:193], v[0:3]
	v_mfma_f32_16x16x32_bf16 v[44:47], v[202:205], v[170:173], v[44:47]
	v_mfma_f32_16x16x32_bf16 v[40:43], v[214:217], v[170:173], v[40:43]
	v_mfma_f32_16x16x32_bf16 v[28:31], v[202:205], v[178:181], v[28:31]
	v_mfma_f32_16x16x32_bf16 v[24:27], v[214:217], v[178:181], v[24:27]
	v_mfma_f32_16x16x32_bf16 v[12:15], v[202:205], v[186:189], v[12:15]
	v_mfma_f32_16x16x32_bf16 v[8:11], v[214:217], v[186:189], v[8:11]
	v_mfma_f32_16x16x32_bf16 v[4:7], v[202:205], v[194:197], v[4:7]
	v_mfma_f32_16x16x32_bf16 v[0:3], v[214:217], v[194:197], v[0:3]
	s_setprio 1
	s_add_i32 s45, 0, 0x18000
	v_add_u32_e32 v162, s45, v146
	s_barrier
	ds_read_b128 v[150:153], v162
	ds_read_b128 v[154:157], v162 offset:1024
	ds_read_b128 v[158:161], v162 offset:2048
	ds_read_b128 v[162:165], v162 offset:3072
	s_add_u32 s14, s20, 0xe0000
	s_addc_u32 s15, s21, 0
	s_mov_b32 m0, s26
	v_lshl_add_u64 v[198:199], s[14:15], 0, v[128:129]
	ds_read_b128 v[166:169], v148 offset:32768
	ds_read_b128 v[170:173], v148 offset:33792
	ds_read_b128 v[174:177], v148 offset:34816
	ds_read_b128 v[178:181], v148 offset:35840
	ds_read_b128 v[182:185], v148 offset:36864
	ds_read_b128 v[186:189], v148 offset:37888
	ds_read_b128 v[190:193], v148 offset:38912
	ds_read_b128 v[194:197], v148 offset:39936
	global_load_lds_dwordx4 v[198:199], off
	v_lshl_add_u64 v[198:199], s[14:15], 0, v[132:133]
	s_mov_b32 m0, s27
	s_nop 0
	global_load_lds_dwordx4 v[198:199], off
	s_waitcnt lgkmcnt(8)
	s_barrier
	s_waitcnt lgkmcnt(0)
	s_setprio 0
	s_waitcnt lgkmcnt(0)
	v_mfma_f32_16x16x32_bf16 v[124:127], v[150:153], v[166:169], v[124:127]
	v_mfma_f32_16x16x32_bf16 v[120:123], v[158:161], v[166:169], v[120:123]
	v_mfma_f32_16x16x32_bf16 v[116:119], v[150:153], v[174:177], v[116:119]
	v_mfma_f32_16x16x32_bf16 v[112:115], v[158:161], v[174:177], v[112:115]
	v_mfma_f32_16x16x32_bf16 v[100:103], v[150:153], v[182:185], v[100:103]
	v_mfma_f32_16x16x32_bf16 v[96:99], v[158:161], v[182:185], v[96:99]
	v_mfma_f32_16x16x32_bf16 v[84:87], v[150:153], v[190:193], v[84:87]
	v_mfma_f32_16x16x32_bf16 v[80:83], v[158:161], v[190:193], v[80:83]
	v_mfma_f32_16x16x32_bf16 v[124:127], v[154:157], v[170:173], v[124:127]
	v_mfma_f32_16x16x32_bf16 v[120:123], v[162:165], v[170:173], v[120:123]
	v_mfma_f32_16x16x32_bf16 v[116:119], v[154:157], v[178:181], v[116:119]
	v_mfma_f32_16x16x32_bf16 v[112:115], v[162:165], v[178:181], v[112:115]
	v_mfma_f32_16x16x32_bf16 v[100:103], v[154:157], v[186:189], v[100:103]
	v_mfma_f32_16x16x32_bf16 v[96:99], v[162:165], v[186:189], v[96:99]
	v_mfma_f32_16x16x32_bf16 v[84:87], v[154:157], v[194:197], v[84:87]
	v_mfma_f32_16x16x32_bf16 v[80:83], v[162:165], v[194:197], v[80:83]
	s_setprio 1
	s_barrier
	s_add_i32 s20, 0, 0x1c000
	s_add_i32 s14, s45, s23
	v_add_u32_e32 v214, s20, v146
	v_lshl_add_u64 v[206:207], v[206:207], 0, s[8:9]
	s_mov_b32 m0, s14
	ds_read_b128 v[198:201], v214
	ds_read_b128 v[202:205], v214 offset:1024
	ds_read_b128 v[210:213], v214 offset:2048
	ds_read_b128 v[214:217], v214 offset:3072
	global_load_lds_dwordx4 v[206:207], off
	v_lshl_add_u64 v[206:207], v[218:219], 0, s[8:9]
	s_add_i32 m0, s14, 0x2000
	s_nop 0
	global_load_lds_dwordx4 v[206:207], off
	s_barrier
	s_waitcnt lgkmcnt(0)
	s_setprio 0
	s_waitcnt lgkmcnt(0)
	v_mfma_f32_16x16x32_bf16 v[108:111], v[198:201], v[166:169], v[108:111]
	v_mfma_f32_16x16x32_bf16 v[104:107], v[210:213], v[166:169], v[104:107]
	v_mfma_f32_16x16x32_bf16 v[92:95], v[198:201], v[174:177], v[92:95]
	v_mfma_f32_16x16x32_bf16 v[88:91], v[210:213], v[174:177], v[88:91]
	v_mfma_f32_16x16x32_bf16 v[76:79], v[198:201], v[182:185], v[76:79]
	v_mfma_f32_16x16x32_bf16 v[72:75], v[210:213], v[182:185], v[72:75]
	v_mfma_f32_16x16x32_bf16 v[68:71], v[198:201], v[190:193], v[68:71]
	v_mfma_f32_16x16x32_bf16 v[64:67], v[210:213], v[190:193], v[64:67]
	v_mfma_f32_16x16x32_bf16 v[108:111], v[202:205], v[170:173], v[108:111]
	v_mfma_f32_16x16x32_bf16 v[104:107], v[214:217], v[170:173], v[104:107]
	v_mfma_f32_16x16x32_bf16 v[92:95], v[202:205], v[178:181], v[92:95]
	v_mfma_f32_16x16x32_bf16 v[88:91], v[214:217], v[178:181], v[88:91]
	v_mfma_f32_16x16x32_bf16 v[76:79], v[202:205], v[186:189], v[76:79]
	v_mfma_f32_16x16x32_bf16 v[72:75], v[214:217], v[186:189], v[72:75]
	v_mfma_f32_16x16x32_bf16 v[68:71], v[202:205], v[194:197], v[68:71]
	v_mfma_f32_16x16x32_bf16 v[64:67], v[214:217], v[194:197], v[64:67]
	s_setprio 1
	s_mov_b32 m0, s31
	v_lshl_add_u64 v[206:207], v[220:221], 0, s[8:9]
	s_barrier
	ds_read_b128 v[166:169], v148 offset:49152
	ds_read_b128 v[170:173], v148 offset:50176
	ds_read_b128 v[174:177], v148 offset:51200
	ds_read_b128 v[178:181], v148 offset:52224
	ds_read_b128 v[182:185], v148 offset:53248
	ds_read_b128 v[186:189], v148 offset:54272
	ds_read_b128 v[190:193], v148 offset:55296
	ds_read_b128 v[194:197], v148 offset:56320
	global_load_lds_dwordx4 v[206:207], off
	v_lshl_add_u64 v[206:207], v[222:223], 0, s[8:9]
	s_mov_b32 m0, s33
	s_nop 0
	global_load_lds_dwordx4 v[206:207], off
	s_barrier
	s_waitcnt lgkmcnt(0)
	s_setprio 0
	s_waitcnt lgkmcnt(0)
	v_mfma_f32_16x16x32_bf16 v[60:63], v[150:153], v[166:169], v[60:63]
	v_mfma_f32_16x16x32_bf16 v[56:59], v[158:161], v[166:169], v[56:59]
	v_mfma_f32_16x16x32_bf16 v[52:55], v[150:153], v[174:177], v[52:55]
	v_mfma_f32_16x16x32_bf16 v[48:51], v[158:161], v[174:177], v[48:51]
	v_mfma_f32_16x16x32_bf16 v[36:39], v[150:153], v[182:185], v[36:39]
	v_mfma_f32_16x16x32_bf16 v[32:35], v[158:161], v[182:185], v[32:35]
	v_mfma_f32_16x16x32_bf16 v[20:23], v[150:153], v[190:193], v[20:23]
	v_mfma_f32_16x16x32_bf16 v[16:19], v[158:161], v[190:193], v[16:19]
	v_mfma_f32_16x16x32_bf16 v[60:63], v[154:157], v[170:173], v[60:63]
	v_mfma_f32_16x16x32_bf16 v[56:59], v[162:165], v[170:173], v[56:59]
	v_mfma_f32_16x16x32_bf16 v[52:55], v[154:157], v[178:181], v[52:55]
	v_mfma_f32_16x16x32_bf16 v[48:51], v[162:165], v[178:181], v[48:51]
	v_mfma_f32_16x16x32_bf16 v[36:39], v[154:157], v[186:189], v[36:39]
	v_mfma_f32_16x16x32_bf16 v[32:35], v[162:165], v[186:189], v[32:35]
	v_mfma_f32_16x16x32_bf16 v[20:23], v[154:157], v[194:197], v[20:23]
	v_mfma_f32_16x16x32_bf16 v[16:19], v[162:165], v[194:197], v[16:19]
	s_setprio 1
	s_barrier
	s_add_u32 s14, s18, 0xe0080
	s_addc_u32 s15, s19, 0
	s_add_i32 s18, s20, s23
	v_lshl_add_u64 v[150:151], s[14:15], 0, v[130:131]
	s_mov_b32 m0, s18
	s_nop 0
	global_load_lds_dwordx4 v[150:151], off
	v_lshl_add_u64 v[150:151], s[14:15], 0, v[134:135]
	s_add_i32 m0, s18, 0x2000
	s_nop 0
	global_load_lds_dwordx4 v[150:151], off
	s_waitcnt vmcnt(6)
	s_barrier
	s_setprio 0
	v_mfma_f32_16x16x32_bf16 v[44:47], v[198:201], v[166:169], v[44:47]
	v_mfma_f32_16x16x32_bf16 v[40:43], v[210:213], v[166:169], v[40:43]
	v_mfma_f32_16x16x32_bf16 v[28:31], v[198:201], v[174:177], v[28:31]
	v_mfma_f32_16x16x32_bf16 v[24:27], v[210:213], v[174:177], v[24:27]
	v_mfma_f32_16x16x32_bf16 v[12:15], v[198:201], v[182:185], v[12:15]
	v_mfma_f32_16x16x32_bf16 v[8:11], v[210:213], v[182:185], v[8:11]
	v_mfma_f32_16x16x32_bf16 v[4:7], v[198:201], v[190:193], v[4:7]
	v_mfma_f32_16x16x32_bf16 v[0:3], v[210:213], v[190:193], v[0:3]
	v_mfma_f32_16x16x32_bf16 v[44:47], v[202:205], v[170:173], v[44:47]
	v_mfma_f32_16x16x32_bf16 v[40:43], v[214:217], v[170:173], v[40:43]
	v_mfma_f32_16x16x32_bf16 v[28:31], v[202:205], v[178:181], v[28:31]
	v_mfma_f32_16x16x32_bf16 v[24:27], v[214:217], v[178:181], v[24:27]
	v_mfma_f32_16x16x32_bf16 v[12:15], v[202:205], v[186:189], v[12:15]
	v_mfma_f32_16x16x32_bf16 v[8:11], v[214:217], v[186:189], v[8:11]
	v_mfma_f32_16x16x32_bf16 v[4:7], v[202:205], v[194:197], v[4:7]
	v_mfma_f32_16x16x32_bf16 v[0:3], v[214:217], v[194:197], v[0:3]
	s_setprio 1
	s_add_i32 s44, s44, 2
	s_add_u32 s42, s42, 0x100
	s_addc_u32 s43, s43, 0
	s_cmp_gt_u32 s44, 53
	s_mov_b64 s[14:15], s[16:17]
	s_barrier
	s_cbranch_scc0 .LBB0_974
	v_mov_b32_e32 v150, v145
	v_mov_b32_e32 v151, v144
	s_lshl_b32 s14, s34, 8
	s_add_i32 s14, s14, s29
	v_add_u32_e32 v150, s14, v150
	s_lshl_b32 s14, s41, 8
	s_or_b32 s14, s14, s30
	v_lshl_add_u32 v152, v151, 3, s14
	v_ashrrev_i32_e32 v151, 31, v150
	v_lshlrev_b64 v[150:151], 12, v[150:151]
	v_ashrrev_i32_e32 v153, 31, v152
	v_lshl_add_u64 v[150:151], s[10:11], 0, v[150:151]
	v_lshl_add_u64 v[150:151], v[152:153], 1, v[150:151]
	v_cvt_pk_bf16_f32 v108, v108, v109
	v_cvt_pk_bf16_f32 v109, v110, v111
	v_cvt_pk_bf16_f32 v110, v104, v105
	v_cvt_pk_bf16_f32 v111, v106, v107
	s_mov_b64 s[14:15], 0x10000
	global_store_dwordx4 v[150:151], v[108:111], off offset:256
	v_cvt_pk_bf16_f32 v92, v92, v93
	v_cvt_pk_bf16_f32 v93, v94, v95
	v_lshl_add_u64 v[108:109], v[150:151], 0, s[14:15]
	s_mov_b32 s14, 0x10000
	v_add_co_u32_e32 v110, vcc, s14, v150
	v_cvt_pk_bf16_f32 v94, v88, v89
	v_cvt_pk_bf16_f32 v95, v90, v91
	s_mov_b64 s[14:15], 0x20000
	v_addc_co_u32_e32 v111, vcc, 0, v151, vcc
	global_store_dwordx4 v[108:109], v[92:95], off offset:256
	v_cvt_pk_bf16_f32 v76, v76, v77
	v_cvt_pk_bf16_f32 v77, v78, v79
	v_lshl_add_u64 v[92:93], v[150:151], 0, s[14:15]
	s_mov_b32 s14, 0x20000
	v_add_co_u32_e32 v94, vcc, s14, v150
	v_cvt_pk_bf16_f32 v78, v72, v73
	v_cvt_pk_bf16_f32 v79, v74, v75
	s_mov_b64 s[14:15], 0x30000
	v_addc_co_u32_e32 v95, vcc, 0, v151, vcc
	global_store_dwordx4 v[92:93], v[76:79], off offset:256
	v_cvt_pk_bf16_f32 v68, v68, v69
	v_cvt_pk_bf16_f32 v69, v70, v71
	v_lshl_add_u64 v[76:77], v[150:151], 0, s[14:15]
	s_mov_b32 s14, 0x30000
	v_add_co_u32_e32 v78, vcc, s14, v150
	s_mov_b64 s[14:15], 0x80000
	s_nop 0
	v_addc_co_u32_e32 v79, vcc, 0, v151, vcc
	v_cvt_pk_bf16_f32 v70, v64, v65
	v_lshl_add_u64 v[64:65], v[150:151], 0, s[14:15]
	s_mov_b32 s14, 0x80000
	v_cvt_pk_bf16_f32 v60, v60, v61
	v_cvt_pk_bf16_f32 v61, v62, v63
	v_cvt_pk_bf16_f32 v62, v56, v57
	v_add_co_u32_e32 v56, vcc, s14, v150
	v_cvt_pk_bf16_f32 v44, v44, v45
	v_cvt_pk_bf16_f32 v45, v46, v47
	v_cvt_pk_bf16_f32 v46, v40, v41
	v_cvt_pk_bf16_f32 v47, v42, v43
	s_mov_b64 s[14:15], 0x90000
	v_addc_co_u32_e32 v57, vcc, 0, v151, vcc
	global_store_dwordx4 v[64:65], v[44:47], off offset:256
	v_cvt_pk_bf16_f32 v28, v28, v29
	v_cvt_pk_bf16_f32 v29, v30, v31
	v_lshl_add_u64 v[44:45], v[150:151], 0, s[14:15]
	s_mov_b32 s14, 0x90000
	v_add_co_u32_e32 v46, vcc, s14, v150
	v_cvt_pk_bf16_f32 v30, v24, v25
	s_nop 0
	v_addc_co_u32_e32 v47, vcc, 0, v151, vcc
	v_cvt_pk_bf16_f32 v31, v26, v27
	global_store_dwordx4 v[44:45], v[28:31], off offset:256
	s_mov_b64 s[14:15], 0xa0000
	v_cvt_pk_bf16_f32 v12, v12, v13
	v_add_co_u32_e32 v30, vcc, s37, v150
	v_lshl_add_u64 v[28:29], v[150:151], 0, s[14:15]
	s_nop 0
	v_addc_co_u32_e32 v31, vcc, 0, v151, vcc
	v_cvt_pk_bf16_f32 v13, v14, v15
	v_cvt_pk_bf16_f32 v14, v8, v9
	v_cvt_pk_bf16_f32 v15, v10, v11
	global_store_dwordx4 v[28:29], v[12:15], off offset:256
	v_cvt_pk_bf16_f32 v124, v124, v125
	v_cvt_pk_bf16_f32 v125, v126, v127
	v_add_co_u32_e32 v14, vcc, s38, v150
	v_cvt_pk_bf16_f32 v126, v120, v121
	s_nop 0
	v_addc_co_u32_e32 v15, vcc, 0, v151, vcc
	v_cvt_pk_bf16_f32 v127, v122, v123
	v_cvt_pk_bf16_f32 v104, v116, v117
	v_cvt_pk_bf16_f32 v105, v118, v119
	v_cvt_pk_bf16_f32 v106, v112, v113
	v_cvt_pk_bf16_f32 v107, v114, v115
	v_cvt_pk_bf16_f32 v88, v100, v101
	v_cvt_pk_bf16_f32 v89, v102, v103
	v_cvt_pk_bf16_f32 v90, v96, v97
	v_cvt_pk_bf16_f32 v91, v98, v99
	v_cvt_pk_bf16_f32 v72, v84, v85
	v_cvt_pk_bf16_f32 v73, v86, v87
	v_cvt_pk_bf16_f32 v74, v80, v81
	v_cvt_pk_bf16_f32 v75, v82, v83
	v_cvt_pk_bf16_f32 v71, v66, v67
	v_cvt_pk_bf16_f32 v63, v58, v59
	v_cvt_pk_bf16_f32 v40, v52, v53
	v_cvt_pk_bf16_f32 v41, v54, v55
	v_cvt_pk_bf16_f32 v42, v48, v49
	v_cvt_pk_bf16_f32 v43, v50, v51
	v_cvt_pk_bf16_f32 v24, v36, v37
	v_cvt_pk_bf16_f32 v25, v38, v39
	v_cvt_pk_bf16_f32 v26, v32, v33
	v_cvt_pk_bf16_f32 v27, v34, v35
	v_lshl_add_u64 v[12:13], v[150:151], 0, s[12:13]
	v_cvt_pk_bf16_f32 v8, v20, v21
	v_cvt_pk_bf16_f32 v9, v22, v23
	v_cvt_pk_bf16_f32 v10, v16, v17
	v_cvt_pk_bf16_f32 v11, v18, v19
	v_cvt_pk_bf16_f32 v4, v4, v5
	v_cvt_pk_bf16_f32 v5, v6, v7
	v_cvt_pk_bf16_f32 v6, v0, v1
	v_cvt_pk_bf16_f32 v7, v2, v3
	s_and_b64 vcc, exec, s[0:1]
	s_mov_b32 s41, s39
	s_mov_b32 s34, s40
	s_mov_b64 s[16:17], s[4:5]
	s_mov_b64 s[14:15], s[2:3]
	global_store_dwordx4 v[150:151], v[124:127], off
	global_store_dwordx4 v[110:111], v[104:107], off
	global_store_dwordx4 v[94:95], v[88:91], off
	global_store_dwordx4 v[78:79], v[72:75], off
	global_store_dwordx4 v[76:77], v[68:71], off offset:256
	global_store_dwordx4 v[56:57], v[60:63], off
	global_store_dwordx4 v[46:47], v[40:43], off
	global_store_dwordx4 v[30:31], v[24:27], off
	global_store_dwordx4 v[14:15], v[8:11], off
	global_store_dwordx4 v[12:13], v[4:7], off offset:256
	s_cbranch_vccz .LBB0_963
	s_waitcnt vmcnt(0)
	s_cmpk_gt_u32 s22, 0xff
	s_cbranch_scc1 .LBB0_978
	s_barrier

.LBB0_1200:
	s_waitcnt lgkmcnt(0)
	ds_read_b128 v[144:147], v151
	ds_read_b128 v[156:159], v151 offset:1024
	ds_read_b128 v[160:163], v151 offset:2048
	ds_read_b128 v[164:167], v151 offset:3072
	s_add_u32 s30, s28, 0xfff80080
	s_addc_u32 s31, s29, -1
	s_cmp_eq_u32 s56, 28
	s_cselect_b32 s35, s4, s31
	s_cselect_b32 s34, s7, s30
	s_cselect_b32 s31, s21, s55
	s_cselect_b32 s30, s23, s54
	v_lshl_add_u64 v[200:201], s[28:29], 0, v[136:137]
	s_add_i32 m0, s17, 0xc000
	ds_read_b128 v[168:171], v152
	ds_read_b128 v[172:175], v152 offset:1024
	ds_read_b128 v[176:179], v152 offset:2048
	ds_read_b128 v[180:183], v152 offset:3072
	ds_read_b128 v[184:187], v152 offset:4096
	ds_read_b128 v[188:191], v152 offset:5120
	ds_read_b128 v[192:195], v152 offset:6144
	ds_read_b128 v[196:199], v152 offset:7168
	global_load_lds_dwordx4 v[200:201], off
	v_lshl_add_u64 v[200:201], s[28:29], 0, v[138:139]
	s_add_i32 m0, s17, 0xe000
	s_nop 0
	global_load_lds_dwordx4 v[200:201], off
	s_waitcnt lgkmcnt(8)
	s_barrier
	s_waitcnt lgkmcnt(0)
	s_setprio 0
	s_waitcnt lgkmcnt(0)
	v_mfma_f32_16x16x32_bf16 v[124:127], v[144:147], v[168:171], v[124:127]
	v_mfma_f32_16x16x32_bf16 v[120:123], v[160:163], v[168:171], v[120:123]
	v_mfma_f32_16x16x32_bf16 v[116:119], v[144:147], v[176:179], v[116:119]
	v_mfma_f32_16x16x32_bf16 v[112:115], v[160:163], v[176:179], v[112:115]
	v_mfma_f32_16x16x32_bf16 v[100:103], v[144:147], v[184:187], v[100:103]
	v_mfma_f32_16x16x32_bf16 v[96:99], v[160:163], v[184:187], v[96:99]
	v_mfma_f32_16x16x32_bf16 v[84:87], v[144:147], v[192:195], v[84:87]
	v_mfma_f32_16x16x32_bf16 v[80:83], v[160:163], v[192:195], v[80:83]
	v_mfma_f32_16x16x32_bf16 v[124:127], v[156:159], v[172:175], v[124:127]
	v_mfma_f32_16x16x32_bf16 v[120:123], v[164:167], v[172:175], v[120:123]
	v_mfma_f32_16x16x32_bf16 v[116:119], v[156:159], v[180:183], v[116:119]
	v_mfma_f32_16x16x32_bf16 v[112:115], v[164:167], v[180:183], v[112:115]
	v_mfma_f32_16x16x32_bf16 v[100:103], v[156:159], v[188:191], v[100:103]
	v_mfma_f32_16x16x32_bf16 v[96:99], v[164:167], v[188:191], v[96:99]
	v_mfma_f32_16x16x32_bf16 v[84:87], v[156:159], v[196:199], v[84:87]
	v_mfma_f32_16x16x32_bf16 v[80:83], v[164:167], v[196:199], v[80:83]
	s_setprio 1
	s_barrier
	s_add_i32 s57, s45, s33
	v_lshl_add_u64 v[218:219], s[30:31], 0, v[130:131]
	s_mov_b32 m0, s57
	ds_read_b128 v[200:203], v153
	ds_read_b128 v[204:207], v153 offset:1024
	ds_read_b128 v[210:213], v153 offset:2048
	ds_read_b128 v[214:217], v153 offset:3072
	global_load_lds_dwordx4 v[218:219], off
	v_lshl_add_u64 v[220:221], s[30:31], 0, v[134:135]
	s_add_i32 m0, s57, 0x2000
	s_nop 0
	global_load_lds_dwordx4 v[220:221], off
	s_barrier
	s_waitcnt lgkmcnt(0)
	s_setprio 0
	s_waitcnt lgkmcnt(0)
	v_mfma_f32_16x16x32_bf16 v[108:111], v[200:203], v[168:171], v[108:111]
	v_mfma_f32_16x16x32_bf16 v[104:107], v[210:213], v[168:171], v[104:107]
	v_mfma_f32_16x16x32_bf16 v[92:95], v[200:203], v[176:179], v[92:95]
	v_mfma_f32_16x16x32_bf16 v[88:91], v[210:213], v[176:179], v[88:91]
	v_mfma_f32_16x16x32_bf16 v[76:79], v[200:203], v[184:187], v[76:79]
	v_mfma_f32_16x16x32_bf16 v[72:75], v[210:213], v[184:187], v[72:75]
	v_mfma_f32_16x16x32_bf16 v[68:71], v[200:203], v[192:195], v[68:71]
	v_mfma_f32_16x16x32_bf16 v[64:67], v[210:213], v[192:195], v[64:67]
	v_mfma_f32_16x16x32_bf16 v[108:111], v[204:207], v[172:175], v[108:111]
	v_mfma_f32_16x16x32_bf16 v[104:107], v[214:217], v[172:175], v[104:107]
	v_mfma_f32_16x16x32_bf16 v[92:95], v[204:207], v[180:183], v[92:95]
	v_mfma_f32_16x16x32_bf16 v[88:91], v[214:217], v[180:183], v[88:91]
	v_mfma_f32_16x16x32_bf16 v[76:79], v[204:207], v[188:191], v[76:79]
	v_mfma_f32_16x16x32_bf16 v[72:75], v[214:217], v[188:191], v[72:75]
	v_mfma_f32_16x16x32_bf16 v[68:71], v[204:207], v[196:199], v[68:71]
	v_mfma_f32_16x16x32_bf16 v[64:67], v[214:217], v[196:199], v[64:67]
	s_setprio 1
	s_mov_b32 m0, s17
	v_lshl_add_u64 v[222:223], s[34:35], 0, v[128:129]
	s_barrier
	ds_read_b128 v[168:171], v152 offset:16384
	ds_read_b128 v[172:175], v152 offset:17408
	ds_read_b128 v[176:179], v152 offset:18432
	ds_read_b128 v[180:183], v152 offset:19456
	ds_read_b128 v[184:187], v152 offset:20480
	ds_read_b128 v[188:191], v152 offset:21504
	ds_read_b128 v[192:195], v152 offset:22528
	ds_read_b128 v[196:199], v152 offset:23552
	global_load_lds_dwordx4 v[222:223], off
	v_lshl_add_u64 v[224:225], s[34:35], 0, v[132:133]
	s_mov_b32 m0, s38
	s_nop 0
	global_load_lds_dwordx4 v[224:225], off
	s_barrier
	s_waitcnt lgkmcnt(0)
	s_setprio 0
	s_waitcnt lgkmcnt(0)
	v_mfma_f32_16x16x32_bf16 v[60:63], v[144:147], v[168:171], v[60:63]
	v_mfma_f32_16x16x32_bf16 v[56:59], v[160:163], v[168:171], v[56:59]
	v_mfma_f32_16x16x32_bf16 v[52:55], v[144:147], v[176:179], v[52:55]
	v_mfma_f32_16x16x32_bf16 v[48:51], v[160:163], v[176:179], v[48:51]
	v_mfma_f32_16x16x32_bf16 v[36:39], v[144:147], v[184:187], v[36:39]
	v_mfma_f32_16x16x32_bf16 v[32:35], v[160:163], v[184:187], v[32:35]
	v_mfma_f32_16x16x32_bf16 v[20:23], v[144:147], v[192:195], v[20:23]
	v_mfma_f32_16x16x32_bf16 v[16:19], v[160:163], v[192:195], v[16:19]
	v_mfma_f32_16x16x32_bf16 v[60:63], v[156:159], v[172:175], v[60:63]
	v_mfma_f32_16x16x32_bf16 v[56:59], v[164:167], v[172:175], v[56:59]
	v_mfma_f32_16x16x32_bf16 v[52:55], v[156:159], v[180:183], v[52:55]
	v_mfma_f32_16x16x32_bf16 v[48:51], v[164:167], v[180:183], v[48:51]
	v_mfma_f32_16x16x32_bf16 v[36:39], v[156:159], v[188:191], v[36:39]
	v_mfma_f32_16x16x32_bf16 v[32:35], v[164:167], v[188:191], v[32:35]
	v_mfma_f32_16x16x32_bf16 v[20:23], v[156:159], v[196:199], v[20:23]
	v_mfma_f32_16x16x32_bf16 v[16:19], v[164:167], v[196:199], v[16:19]
	s_setprio 1
	s_barrier
	s_add_u32 s60, s30, 0x80000
	s_addc_u32 s61, s31, 0
	s_add_i32 s57, s51, s33
	v_lshl_add_u64 v[144:145], s[60:61], 0, v[130:131]
	s_mov_b32 m0, s57
	s_nop 0
	global_load_lds_dwordx4 v[144:145], off
	v_lshl_add_u64 v[144:145], s[60:61], 0, v[134:135]
	s_add_i32 m0, s57, 0x2000
	s_nop 0
	global_load_lds_dwordx4 v[144:145], off
	s_waitcnt vmcnt(6)
	s_barrier
	s_setprio 0
	v_mfma_f32_16x16x32_bf16 v[44:47], v[200:203], v[168:171], v[44:47]
	v_mfma_f32_16x16x32_bf16 v[40:43], v[210:213], v[168:171], v[40:43]
	v_mfma_f32_16x16x32_bf16 v[28:31], v[200:203], v[176:179], v[28:31]
	v_mfma_f32_16x16x32_bf16 v[24:27], v[210:213], v[176:179], v[24:27]
	v_mfma_f32_16x16x32_bf16 v[12:15], v[200:203], v[184:187], v[12:15]
	v_mfma_f32_16x16x32_bf16 v[8:11], v[210:213], v[184:187], v[8:11]
	v_mfma_f32_16x16x32_bf16 v[4:7], v[200:203], v[192:195], v[4:7]
	v_mfma_f32_16x16x32_bf16 v[0:3], v[210:213], v[192:195], v[0:3]
	v_mfma_f32_16x16x32_bf16 v[44:47], v[204:207], v[172:175], v[44:47]
	v_mfma_f32_16x16x32_bf16 v[40:43], v[214:217], v[172:175], v[40:43]
	v_mfma_f32_16x16x32_bf16 v[28:31], v[204:207], v[180:183], v[28:31]
	v_mfma_f32_16x16x32_bf16 v[24:27], v[214:217], v[180:183], v[24:27]
	v_mfma_f32_16x16x32_bf16 v[12:15], v[204:207], v[188:191], v[12:15]
	v_mfma_f32_16x16x32_bf16 v[8:11], v[214:217], v[188:191], v[8:11]
	v_mfma_f32_16x16x32_bf16 v[4:7], v[204:207], v[196:199], v[4:7]
	v_mfma_f32_16x16x32_bf16 v[0:3], v[214:217], v[196:199], v[0:3]
	s_setprio 1
	s_add_i32 s57, 0, 0x18000
	v_add_u32_e32 v155, s57, v150
	s_barrier
	ds_read_b128 v[144:147], v155
	ds_read_b128 v[156:159], v155 offset:1024
	ds_read_b128 v[160:163], v155 offset:2048
	ds_read_b128 v[164:167], v155 offset:3072
	s_add_u32 s34, s34, 0x80000
	s_addc_u32 s35, s35, 0
	s_mov_b32 m0, s39
	v_lshl_add_u64 v[200:201], s[34:35], 0, v[128:129]
	ds_read_b128 v[168:171], v152 offset:32768
	ds_read_b128 v[172:175], v152 offset:33792
	ds_read_b128 v[176:179], v152 offset:34816
	ds_read_b128 v[180:183], v152 offset:35840
	ds_read_b128 v[184:187], v152 offset:36864
	ds_read_b128 v[188:191], v152 offset:37888
	ds_read_b128 v[192:195], v152 offset:38912
	ds_read_b128 v[196:199], v152 offset:39936
	global_load_lds_dwordx4 v[200:201], off
	v_lshl_add_u64 v[200:201], s[34:35], 0, v[132:133]
	s_mov_b32 m0, s40
	s_nop 0
	global_load_lds_dwordx4 v[200:201], off
	s_waitcnt lgkmcnt(8)
	s_barrier
	s_waitcnt lgkmcnt(0)
	s_setprio 0
	s_waitcnt lgkmcnt(0)
	v_mfma_f32_16x16x32_bf16 v[124:127], v[144:147], v[168:171], v[124:127]
	v_mfma_f32_16x16x32_bf16 v[120:123], v[160:163], v[168:171], v[120:123]
	v_mfma_f32_16x16x32_bf16 v[116:119], v[144:147], v[176:179], v[116:119]
	v_mfma_f32_16x16x32_bf16 v[112:115], v[160:163], v[176:179], v[112:115]
	v_mfma_f32_16x16x32_bf16 v[100:103], v[144:147], v[184:187], v[100:103]
	v_mfma_f32_16x16x32_bf16 v[96:99], v[160:163], v[184:187], v[96:99]
	v_mfma_f32_16x16x32_bf16 v[84:87], v[144:147], v[192:195], v[84:87]
	v_mfma_f32_16x16x32_bf16 v[80:83], v[160:163], v[192:195], v[80:83]
	v_mfma_f32_16x16x32_bf16 v[124:127], v[156:159], v[172:175], v[124:127]
	v_mfma_f32_16x16x32_bf16 v[120:123], v[164:167], v[172:175], v[120:123]
	v_mfma_f32_16x16x32_bf16 v[116:119], v[156:159], v[180:183], v[116:119]
	v_mfma_f32_16x16x32_bf16 v[112:115], v[164:167], v[180:183], v[112:115]
	v_mfma_f32_16x16x32_bf16 v[100:103], v[156:159], v[188:191], v[100:103]
	v_mfma_f32_16x16x32_bf16 v[96:99], v[164:167], v[188:191], v[96:99]
	v_mfma_f32_16x16x32_bf16 v[84:87], v[156:159], v[196:199], v[84:87]
	v_mfma_f32_16x16x32_bf16 v[80:83], v[164:167], v[196:199], v[80:83]
	s_setprio 1
	s_barrier
	s_add_i32 s34, 0, 0x1c000
	s_add_i32 s35, s57, s33
	v_add_u32_e32 v155, s34, v150
	v_lshl_add_u64 v[218:219], v[218:219], 0, s[8:9]
	s_mov_b32 m0, s35
	ds_read_b128 v[200:203], v155
	ds_read_b128 v[204:207], v155 offset:1024
	ds_read_b128 v[210:213], v155 offset:2048
	ds_read_b128 v[214:217], v155 offset:3072
	global_load_lds_dwordx4 v[218:219], off
	v_lshl_add_u64 v[218:219], v[220:221], 0, s[8:9]
	s_add_i32 m0, s35, 0x2000
	s_nop 0
	global_load_lds_dwordx4 v[218:219], off
	s_barrier
	s_waitcnt lgkmcnt(0)
	s_setprio 0
	s_waitcnt lgkmcnt(0)
	v_mfma_f32_16x16x32_bf16 v[108:111], v[200:203], v[168:171], v[108:111]
	v_mfma_f32_16x16x32_bf16 v[104:107], v[210:213], v[168:171], v[104:107]
	v_mfma_f32_16x16x32_bf16 v[92:95], v[200:203], v[176:179], v[92:95]
	v_mfma_f32_16x16x32_bf16 v[88:91], v[210:213], v[176:179], v[88:91]
	v_mfma_f32_16x16x32_bf16 v[76:79], v[200:203], v[184:187], v[76:79]
	v_mfma_f32_16x16x32_bf16 v[72:75], v[210:213], v[184:187], v[72:75]
	v_mfma_f32_16x16x32_bf16 v[68:71], v[200:203], v[192:195], v[68:71]
	v_mfma_f32_16x16x32_bf16 v[64:67], v[210:213], v[192:195], v[64:67]
	v_mfma_f32_16x16x32_bf16 v[108:111], v[204:207], v[172:175], v[108:111]
	v_mfma_f32_16x16x32_bf16 v[104:107], v[214:217], v[172:175], v[104:107]
	v_mfma_f32_16x16x32_bf16 v[92:95], v[204:207], v[180:183], v[92:95]
	v_mfma_f32_16x16x32_bf16 v[88:91], v[214:217], v[180:183], v[88:91]
	v_mfma_f32_16x16x32_bf16 v[76:79], v[204:207], v[188:191], v[76:79]
	v_mfma_f32_16x16x32_bf16 v[72:75], v[214:217], v[188:191], v[72:75]
	v_mfma_f32_16x16x32_bf16 v[68:71], v[204:207], v[196:199], v[68:71]
	v_mfma_f32_16x16x32_bf16 v[64:67], v[214:217], v[196:199], v[64:67]
	s_setprio 1
	s_mov_b32 m0, s43
	v_lshl_add_u64 v[218:219], v[222:223], 0, s[8:9]
	s_barrier
	ds_read_b128 v[168:171], v152 offset:49152
	ds_read_b128 v[172:175], v152 offset:50176
	ds_read_b128 v[176:179], v152 offset:51200
	ds_read_b128 v[180:183], v152 offset:52224
	ds_read_b128 v[184:187], v152 offset:53248
	ds_read_b128 v[188:191], v152 offset:54272
	ds_read_b128 v[192:195], v152 offset:55296
	ds_read_b128 v[196:199], v152 offset:56320
	global_load_lds_dwordx4 v[218:219], off
	v_lshl_add_u64 v[218:219], v[224:225], 0, s[8:9]
	s_mov_b32 m0, s44
	s_nop 0
	global_load_lds_dwordx4 v[218:219], off
	s_barrier
	s_waitcnt lgkmcnt(0)
	s_setprio 0
	s_waitcnt lgkmcnt(0)
	v_mfma_f32_16x16x32_bf16 v[60:63], v[144:147], v[168:171], v[60:63]
	v_mfma_f32_16x16x32_bf16 v[56:59], v[160:163], v[168:171], v[56:59]
	v_mfma_f32_16x16x32_bf16 v[52:55], v[144:147], v[176:179], v[52:55]
	v_mfma_f32_16x16x32_bf16 v[48:51], v[160:163], v[176:179], v[48:51]
	v_mfma_f32_16x16x32_bf16 v[36:39], v[144:147], v[184:187], v[36:39]
	v_mfma_f32_16x16x32_bf16 v[32:35], v[160:163], v[184:187], v[32:35]
	v_mfma_f32_16x16x32_bf16 v[20:23], v[144:147], v[192:195], v[20:23]
	v_mfma_f32_16x16x32_bf16 v[16:19], v[160:163], v[192:195], v[16:19]
	v_mfma_f32_16x16x32_bf16 v[60:63], v[156:159], v[172:175], v[60:63]
	v_mfma_f32_16x16x32_bf16 v[56:59], v[164:167], v[172:175], v[56:59]
	v_mfma_f32_16x16x32_bf16 v[52:55], v[156:159], v[180:183], v[52:55]
	v_mfma_f32_16x16x32_bf16 v[48:51], v[164:167], v[180:183], v[48:51]
	v_mfma_f32_16x16x32_bf16 v[36:39], v[156:159], v[188:191], v[36:39]
	v_mfma_f32_16x16x32_bf16 v[32:35], v[164:167], v[188:191], v[32:35]
	v_mfma_f32_16x16x32_bf16 v[20:23], v[156:159], v[196:199], v[20:23]
	v_mfma_f32_16x16x32_bf16 v[16:19], v[164:167], v[196:199], v[16:19]
	s_setprio 1
	s_barrier
	s_add_u32 s30, s30, 0x80080
	s_addc_u32 s31, s31, 0
	s_add_i32 s34, s34, s33
	v_lshl_add_u64 v[144:145], s[30:31], 0, v[130:131]
	s_mov_b32 m0, s34
	s_nop 0
	global_load_lds_dwordx4 v[144:145], off
	v_lshl_add_u64 v[144:145], s[30:31], 0, v[134:135]
	s_add_i32 m0, s34, 0x2000
	s_nop 0
	global_load_lds_dwordx4 v[144:145], off
	s_waitcnt vmcnt(6)
	s_barrier
	s_setprio 0
	v_mfma_f32_16x16x32_bf16 v[44:47], v[200:203], v[168:171], v[44:47]
	v_mfma_f32_16x16x32_bf16 v[40:43], v[210:213], v[168:171], v[40:43]
	v_mfma_f32_16x16x32_bf16 v[28:31], v[200:203], v[176:179], v[28:31]
	v_mfma_f32_16x16x32_bf16 v[24:27], v[210:213], v[176:179], v[24:27]
	v_mfma_f32_16x16x32_bf16 v[12:15], v[200:203], v[184:187], v[12:15]
	v_mfma_f32_16x16x32_bf16 v[8:11], v[210:213], v[184:187], v[8:11]
	v_mfma_f32_16x16x32_bf16 v[4:7], v[200:203], v[192:195], v[4:7]
	v_mfma_f32_16x16x32_bf16 v[0:3], v[210:213], v[192:195], v[0:3]
	v_mfma_f32_16x16x32_bf16 v[44:47], v[204:207], v[172:175], v[44:47]
	v_mfma_f32_16x16x32_bf16 v[40:43], v[214:217], v[172:175], v[40:43]
	v_mfma_f32_16x16x32_bf16 v[28:31], v[204:207], v[180:183], v[28:31]
	v_mfma_f32_16x16x32_bf16 v[24:27], v[214:217], v[180:183], v[24:27]
	v_mfma_f32_16x16x32_bf16 v[12:15], v[204:207], v[188:191], v[12:15]
	v_mfma_f32_16x16x32_bf16 v[8:11], v[214:217], v[188:191], v[8:11]
	v_mfma_f32_16x16x32_bf16 v[4:7], v[204:207], v[196:199], v[4:7]
	v_mfma_f32_16x16x32_bf16 v[0:3], v[214:217], v[196:199], v[0:3]
	s_setprio 1
	s_add_i32 s56, s56, 2
	s_add_u32 s28, s28, 0x100
	s_addc_u32 s29, s29, 0
	s_add_u32 s54, s54, 0x100
	s_addc_u32 s55, s55, 0
	s_cmp_gt_u32 s56, 29
	s_barrier
	s_cbranch_scc0 .LBB0_1200
	v_mov_b32_e32 v155, v148
	v_mov_b32_e32 v156, v149
	s_cmp_gt_i32 s6, 7
	s_mov_b64 s[28:29], -1
	s_cbranch_scc0 .LBB0_1231
	s_cmp_gt_u32 s6, 15
	s_cbranch_scc0 .LBB0_1212
	s_cmp_gt_u32 s6, 23
	s_cbranch_scc0 .LBB0_1209
	s_lshl_b32 s4, s16, 8
	s_add_i32 s4, s4, s41
	v_lshl_add_u32 v144, v156, 3, s42
	v_add_u32_e32 v157, s4, v155
	v_ashrrev_i32_e32 v145, 31, v144
	v_mad_i64_i32 v[146:147], s[28:29], v157, s52, 0
	s_cmp_gt_u32 s6, 25
	s_mov_b64 s[28:29], -1
	v_lshl_add_u64 v[146:147], s[14:15], 0, v[146:147]
	v_lshlrev_b64 v[144:145], 1, v[144:145]
	v_add_u32_e32 v163, 16, v157
	v_add_u32_e32 v162, 32, v157
	v_add_u32_e32 v161, 48, v157
	v_add_u32_e32 v160, 0x80, v157
	v_add_u32_e32 v159, 0x90, v157
	v_add_u32_e32 v158, 0xa0, v157
	v_add_u32_e32 v157, 0xb0, v157
	s_cbranch_scc0 .LBB0_1206
	s_lshl_b32 s4, s6, 9
	v_lshl_add_u64 v[168:169], v[146:147], 0, s[4:5]
	v_cvt_pk_bf16_f32 v164, v124, v125
	v_cvt_pk_bf16_f32 v165, v126, v127
	v_cvt_pk_bf16_f32 v166, v120, v121
	v_cvt_pk_bf16_f32 v167, v122, v123
	v_lshl_add_u64 v[168:169], v[168:169], 0, v[144:145]
	global_store_dwordx4 v[168:169], v[164:167], off
	s_nop 1
	v_cvt_pk_bf16_f32 v164, v108, v109
	v_cvt_pk_bf16_f32 v165, v110, v111
	v_cvt_pk_bf16_f32 v166, v104, v105
	v_cvt_pk_bf16_f32 v167, v106, v107
	global_store_dwordx4 v[168:169], v[164:167], off offset:256
	v_mov_b64_e32 v[168:169], s[14:15]
	v_mad_i64_i32 v[170:171], s[28:29], v163, s52, v[168:169]
	v_lshl_add_u64 v[170:171], v[170:171], 0, s[4:5]
	v_cvt_pk_bf16_f32 v164, v116, v117
	v_cvt_pk_bf16_f32 v165, v118, v119
	v_cvt_pk_bf16_f32 v166, v112, v113
	v_cvt_pk_bf16_f32 v167, v114, v115
	v_lshl_add_u64 v[170:171], v[170:171], 0, v[144:145]
	global_store_dwordx4 v[170:171], v[164:167], off
	s_nop 1
	v_cvt_pk_bf16_f32 v164, v92, v93
	v_cvt_pk_bf16_f32 v165, v94, v95
	v_cvt_pk_bf16_f32 v166, v88, v89
	v_cvt_pk_bf16_f32 v167, v90, v91
	global_store_dwordx4 v[170:171], v[164:167], off offset:256
	v_mad_i64_i32 v[170:171], s[28:29], v162, s52, v[168:169]
	v_lshl_add_u64 v[170:171], v[170:171], 0, s[4:5]
	v_cvt_pk_bf16_f32 v164, v100, v101
	v_cvt_pk_bf16_f32 v165, v102, v103
	v_cvt_pk_bf16_f32 v166, v96, v97
	v_cvt_pk_bf16_f32 v167, v98, v99
	v_lshl_add_u64 v[170:171], v[170:171], 0, v[144:145]
	global_store_dwordx4 v[170:171], v[164:167], off
	s_nop 1
	v_cvt_pk_bf16_f32 v164, v76, v77
	v_cvt_pk_bf16_f32 v165, v78, v79
	v_cvt_pk_bf16_f32 v166, v72, v73
	v_cvt_pk_bf16_f32 v167, v74, v75
	global_store_dwordx4 v[170:171], v[164:167], off offset:256
	v_mad_i64_i32 v[170:171], s[28:29], v161, s52, v[168:169]
	v_lshl_add_u64 v[170:171], v[170:171], 0, s[4:5]
	v_cvt_pk_bf16_f32 v164, v84, v85
	v_cvt_pk_bf16_f32 v165, v86, v87
	v_cvt_pk_bf16_f32 v166, v80, v81
	v_cvt_pk_bf16_f32 v167, v82, v83
	v_lshl_add_u64 v[170:171], v[170:171], 0, v[144:145]
	global_store_dwordx4 v[170:171], v[164:167], off
	s_nop 1
	v_cvt_pk_bf16_f32 v164, v68, v69
	v_cvt_pk_bf16_f32 v165, v70, v71
	v_cvt_pk_bf16_f32 v166, v64, v65
	v_cvt_pk_bf16_f32 v167, v66, v67
	global_store_dwordx4 v[170:171], v[164:167], off offset:256
	v_mad_i64_i32 v[170:171], s[28:29], v160, s52, v[168:169]
	v_lshl_add_u64 v[170:171], v[170:171], 0, s[4:5]
	v_cvt_pk_bf16_f32 v164, v60, v61
	v_cvt_pk_bf16_f32 v165, v62, v63
	v_cvt_pk_bf16_f32 v166, v56, v57
	v_cvt_pk_bf16_f32 v167, v58, v59
	v_lshl_add_u64 v[170:171], v[170:171], 0, v[144:145]
	global_store_dwordx4 v[170:171], v[164:167], off
	s_nop 1
	v_cvt_pk_bf16_f32 v164, v44, v45
	v_cvt_pk_bf16_f32 v165, v46, v47
	v_cvt_pk_bf16_f32 v166, v40, v41
	v_cvt_pk_bf16_f32 v167, v42, v43
	global_store_dwordx4 v[170:171], v[164:167], off offset:256
	v_mad_i64_i32 v[170:171], s[28:29], v159, s52, v[168:169]
	v_lshl_add_u64 v[170:171], v[170:171], 0, s[4:5]
	v_cvt_pk_bf16_f32 v164, v52, v53
	v_cvt_pk_bf16_f32 v165, v54, v55
	v_cvt_pk_bf16_f32 v166, v48, v49
	v_cvt_pk_bf16_f32 v167, v50, v51
	v_lshl_add_u64 v[170:171], v[170:171], 0, v[144:145]
	global_store_dwordx4 v[170:171], v[164:167], off
	s_nop 1
	v_cvt_pk_bf16_f32 v164, v28, v29
	v_cvt_pk_bf16_f32 v165, v30, v31
	v_cvt_pk_bf16_f32 v166, v24, v25
	v_cvt_pk_bf16_f32 v167, v26, v27
	global_store_dwordx4 v[170:171], v[164:167], off offset:256
	v_mad_i64_i32 v[170:171], s[28:29], v158, s52, v[168:169]
	v_lshl_add_u64 v[170:171], v[170:171], 0, s[4:5]
	v_cvt_pk_bf16_f32 v164, v36, v37
	v_cvt_pk_bf16_f32 v165, v38, v39
	v_cvt_pk_bf16_f32 v166, v32, v33
	v_cvt_pk_bf16_f32 v167, v34, v35
	v_lshl_add_u64 v[170:171], v[170:171], 0, v[144:145]
	v_mad_i64_i32 v[168:169], s[28:29], v157, s52, v[168:169]
	global_store_dwordx4 v[170:171], v[164:167], off
	v_lshl_add_u64 v[168:169], v[168:169], 0, s[4:5]
	v_lshl_add_u64 v[168:169], v[168:169], 0, v[144:145]
	v_cvt_pk_bf16_f32 v164, v12, v13
	v_cvt_pk_bf16_f32 v165, v14, v15
	v_cvt_pk_bf16_f32 v166, v8, v9
	v_cvt_pk_bf16_f32 v167, v10, v11
	global_store_dwordx4 v[170:171], v[164:167], off offset:256
	s_mov_b64 s[28:29], 0
	s_nop 0
	v_cvt_pk_bf16_f32 v164, v20, v21
	v_cvt_pk_bf16_f32 v165, v22, v23
	v_cvt_pk_bf16_f32 v166, v16, v17
	v_cvt_pk_bf16_f32 v167, v18, v19
	global_store_dwordx4 v[168:169], v[164:167], off
	s_nop 1
	v_cvt_pk_bf16_f32 v164, v4, v5
	v_cvt_pk_bf16_f32 v165, v6, v7
	v_cvt_pk_bf16_f32 v166, v0, v1
	v_cvt_pk_bf16_f32 v167, v2, v3
	global_store_dwordx4 v[168:169], v[164:167], off offset:256

.LBB0_1402:
	ds_read_b128 v[150:153], v147
	ds_read_b128 v[154:157], v147 offset:1024
	ds_read_b128 v[158:161], v147 offset:2048
	ds_read_b128 v[162:165], v147 offset:3072
	s_add_u32 s34, s30, 0x100
	s_addc_u32 s35, s31, 0
	s_cmp_eq_u32 s69, 36
	s_cselect_b32 s39, s5, s35
	s_cselect_b32 s38, s4, s34
	s_cselect_b32 s37, s7, s68
	s_cselect_b32 s36, s6, s67
	v_lshl_add_u64 v[198:199], s[30:31], 0, v[136:137]
	s_add_i32 m0, s41, 0xc000
	ds_read_b128 v[166:169], v148
	ds_read_b128 v[170:173], v148 offset:1024
	ds_read_b128 v[174:177], v148 offset:2048
	ds_read_b128 v[178:181], v148 offset:3072
	ds_read_b128 v[182:185], v148 offset:4096
	ds_read_b128 v[186:189], v148 offset:5120
	ds_read_b128 v[190:193], v148 offset:6144
	ds_read_b128 v[194:197], v148 offset:7168
	global_load_lds_dwordx4 v[198:199], off
	v_lshl_add_u64 v[198:199], s[30:31], 0, v[138:139]
	s_add_i32 m0, s41, 0xe000
	s_nop 0
	global_load_lds_dwordx4 v[198:199], off
	s_waitcnt lgkmcnt(8)
	s_barrier
	s_waitcnt lgkmcnt(0)
	s_setprio 0
	s_waitcnt lgkmcnt(0)
	v_mfma_f32_16x16x32_bf16 v[124:127], v[150:153], v[166:169], v[124:127]
	v_mfma_f32_16x16x32_bf16 v[120:123], v[158:161], v[166:169], v[120:123]
	v_mfma_f32_16x16x32_bf16 v[116:119], v[150:153], v[174:177], v[116:119]
	v_mfma_f32_16x16x32_bf16 v[112:115], v[158:161], v[174:177], v[112:115]
	v_mfma_f32_16x16x32_bf16 v[100:103], v[150:153], v[182:185], v[100:103]
	v_mfma_f32_16x16x32_bf16 v[96:99], v[158:161], v[182:185], v[96:99]
	v_mfma_f32_16x16x32_bf16 v[84:87], v[150:153], v[190:193], v[84:87]
	v_mfma_f32_16x16x32_bf16 v[80:83], v[158:161], v[190:193], v[80:83]
	v_mfma_f32_16x16x32_bf16 v[124:127], v[154:157], v[170:173], v[124:127]
	v_mfma_f32_16x16x32_bf16 v[120:123], v[162:165], v[170:173], v[120:123]
	v_mfma_f32_16x16x32_bf16 v[116:119], v[154:157], v[178:181], v[116:119]
	v_mfma_f32_16x16x32_bf16 v[112:115], v[162:165], v[178:181], v[112:115]
	v_mfma_f32_16x16x32_bf16 v[100:103], v[154:157], v[186:189], v[100:103]
	v_mfma_f32_16x16x32_bf16 v[96:99], v[162:165], v[186:189], v[96:99]
	v_mfma_f32_16x16x32_bf16 v[84:87], v[154:157], v[194:197], v[84:87]
	v_mfma_f32_16x16x32_bf16 v[80:83], v[162:165], v[194:197], v[80:83]
	s_setprio 1
	s_barrier
	s_add_i32 s30, s54, s40
	v_lshl_add_u64 v[206:207], s[36:37], 0, v[130:131]
	s_mov_b32 m0, s30
	ds_read_b128 v[198:201], v149
	ds_read_b128 v[202:205], v149 offset:1024
	ds_read_b128 v[210:213], v149 offset:2048
	ds_read_b128 v[214:217], v149 offset:3072
	global_load_lds_dwordx4 v[206:207], off
	v_lshl_add_u64 v[218:219], s[36:37], 0, v[134:135]
	s_add_i32 m0, s30, 0x2000
	s_nop 0
	global_load_lds_dwordx4 v[218:219], off
	s_barrier
	s_waitcnt lgkmcnt(0)
	s_setprio 0
	s_waitcnt lgkmcnt(0)
	v_mfma_f32_16x16x32_bf16 v[108:111], v[198:201], v[166:169], v[108:111]
	v_mfma_f32_16x16x32_bf16 v[104:107], v[210:213], v[166:169], v[104:107]
	v_mfma_f32_16x16x32_bf16 v[92:95], v[198:201], v[174:177], v[92:95]
	v_mfma_f32_16x16x32_bf16 v[88:91], v[210:213], v[174:177], v[88:91]
	v_mfma_f32_16x16x32_bf16 v[76:79], v[198:201], v[182:185], v[76:79]
	v_mfma_f32_16x16x32_bf16 v[72:75], v[210:213], v[182:185], v[72:75]
	v_mfma_f32_16x16x32_bf16 v[68:71], v[198:201], v[190:193], v[68:71]
	v_mfma_f32_16x16x32_bf16 v[64:67], v[210:213], v[190:193], v[64:67]
	v_mfma_f32_16x16x32_bf16 v[108:111], v[202:205], v[170:173], v[108:111]
	v_mfma_f32_16x16x32_bf16 v[104:107], v[214:217], v[170:173], v[104:107]
	v_mfma_f32_16x16x32_bf16 v[92:95], v[202:205], v[178:181], v[92:95]
	v_mfma_f32_16x16x32_bf16 v[88:91], v[214:217], v[178:181], v[88:91]
	v_mfma_f32_16x16x32_bf16 v[76:79], v[202:205], v[186:189], v[76:79]
	v_mfma_f32_16x16x32_bf16 v[72:75], v[214:217], v[186:189], v[72:75]
	v_mfma_f32_16x16x32_bf16 v[68:71], v[202:205], v[194:197], v[68:71]
	v_mfma_f32_16x16x32_bf16 v[64:67], v[214:217], v[194:197], v[64:67]
	s_setprio 1
	s_mov_b32 m0, s41
	v_lshl_add_u64 v[220:221], s[38:39], 0, v[128:129]
	s_barrier
	ds_read_b128 v[166:169], v148 offset:16384
	ds_read_b128 v[170:173], v148 offset:17408
	ds_read_b128 v[174:177], v148 offset:18432
	ds_read_b128 v[178:181], v148 offset:19456
	ds_read_b128 v[182:185], v148 offset:20480
	ds_read_b128 v[186:189], v148 offset:21504
	ds_read_b128 v[190:193], v148 offset:22528
	ds_read_b128 v[194:197], v148 offset:23552
	global_load_lds_dwordx4 v[220:221], off
	v_lshl_add_u64 v[222:223], s[38:39], 0, v[132:133]
	s_mov_b32 m0, s42
	s_nop 0
	global_load_lds_dwordx4 v[222:223], off
	s_barrier
	s_waitcnt lgkmcnt(0)
	s_setprio 0
	s_waitcnt lgkmcnt(0)
	v_mfma_f32_16x16x32_bf16 v[60:63], v[150:153], v[166:169], v[60:63]
	v_mfma_f32_16x16x32_bf16 v[56:59], v[158:161], v[166:169], v[56:59]
	v_mfma_f32_16x16x32_bf16 v[52:55], v[150:153], v[174:177], v[52:55]
	v_mfma_f32_16x16x32_bf16 v[48:51], v[158:161], v[174:177], v[48:51]
	v_mfma_f32_16x16x32_bf16 v[36:39], v[150:153], v[182:185], v[36:39]
	v_mfma_f32_16x16x32_bf16 v[32:35], v[158:161], v[182:185], v[32:35]
	v_mfma_f32_16x16x32_bf16 v[20:23], v[150:153], v[190:193], v[20:23]
	v_mfma_f32_16x16x32_bf16 v[16:19], v[158:161], v[190:193], v[16:19]
	v_mfma_f32_16x16x32_bf16 v[60:63], v[154:157], v[170:173], v[60:63]
	v_mfma_f32_16x16x32_bf16 v[56:59], v[162:165], v[170:173], v[56:59]
	v_mfma_f32_16x16x32_bf16 v[52:55], v[154:157], v[178:181], v[52:55]
	v_mfma_f32_16x16x32_bf16 v[48:51], v[162:165], v[178:181], v[48:51]
	v_mfma_f32_16x16x32_bf16 v[36:39], v[154:157], v[186:189], v[36:39]
	v_mfma_f32_16x16x32_bf16 v[32:35], v[162:165], v[186:189], v[32:35]
	v_mfma_f32_16x16x32_bf16 v[20:23], v[154:157], v[194:197], v[20:23]
	v_mfma_f32_16x16x32_bf16 v[16:19], v[162:165], v[194:197], v[16:19]
	s_setprio 1
	s_barrier
	s_add_u32 s30, s36, 0xa0000
	s_addc_u32 s31, s37, 0
	s_add_i32 s70, s55, s40
	v_lshl_add_u64 v[150:151], s[30:31], 0, v[130:131]
	s_mov_b32 m0, s70
	s_nop 0
	global_load_lds_dwordx4 v[150:151], off
	v_lshl_add_u64 v[150:151], s[30:31], 0, v[134:135]
	s_add_i32 m0, s70, 0x2000
	s_nop 0
	global_load_lds_dwordx4 v[150:151], off
	s_waitcnt vmcnt(6)
	s_barrier
	s_setprio 0
	v_mfma_f32_16x16x32_bf16 v[44:47], v[198:201], v[166:169], v[44:47]
	v_mfma_f32_16x16x32_bf16 v[40:43], v[210:213], v[166:169], v[40:43]
	v_mfma_f32_16x16x32_bf16 v[28:31], v[198:201], v[174:177], v[28:31]
	v_mfma_f32_16x16x32_bf16 v[24:27], v[210:213], v[174:177], v[24:27]
	v_mfma_f32_16x16x32_bf16 v[12:15], v[198:201], v[182:185], v[12:15]
	v_mfma_f32_16x16x32_bf16 v[8:11], v[210:213], v[182:185], v[8:11]
	v_mfma_f32_16x16x32_bf16 v[4:7], v[198:201], v[190:193], v[4:7]
	v_mfma_f32_16x16x32_bf16 v[0:3], v[210:213], v[190:193], v[0:3]
	v_mfma_f32_16x16x32_bf16 v[44:47], v[202:205], v[170:173], v[44:47]
	v_mfma_f32_16x16x32_bf16 v[40:43], v[214:217], v[170:173], v[40:43]
	v_mfma_f32_16x16x32_bf16 v[28:31], v[202:205], v[178:181], v[28:31]
	v_mfma_f32_16x16x32_bf16 v[24:27], v[214:217], v[178:181], v[24:27]
	v_mfma_f32_16x16x32_bf16 v[12:15], v[202:205], v[186:189], v[12:15]
	v_mfma_f32_16x16x32_bf16 v[8:11], v[214:217], v[186:189], v[8:11]
	v_mfma_f32_16x16x32_bf16 v[4:7], v[202:205], v[194:197], v[4:7]
	v_mfma_f32_16x16x32_bf16 v[0:3], v[214:217], v[194:197], v[0:3]
	s_setprio 1
	s_add_i32 s70, 0, 0x18000
	v_add_u32_e32 v162, s70, v146
	s_barrier
	ds_read_b128 v[150:153], v162
	ds_read_b128 v[154:157], v162 offset:1024
	ds_read_b128 v[158:161], v162 offset:2048
	ds_read_b128 v[162:165], v162 offset:3072
	s_add_u32 s30, s38, 0xa0000
	s_addc_u32 s31, s39, 0
	s_mov_b32 m0, s43
	v_lshl_add_u64 v[198:199], s[30:31], 0, v[128:129]
	ds_read_b128 v[166:169], v148 offset:32768
	ds_read_b128 v[170:173], v148 offset:33792
	ds_read_b128 v[174:177], v148 offset:34816
	ds_read_b128 v[178:181], v148 offset:35840
	ds_read_b128 v[182:185], v148 offset:36864
	ds_read_b128 v[186:189], v148 offset:37888
	ds_read_b128 v[190:193], v148 offset:38912
	ds_read_b128 v[194:197], v148 offset:39936
	global_load_lds_dwordx4 v[198:199], off
	v_lshl_add_u64 v[198:199], s[30:31], 0, v[132:133]
	s_mov_b32 m0, s44
	s_nop 0
	global_load_lds_dwordx4 v[198:199], off
	s_waitcnt lgkmcnt(8)
	s_barrier
	s_waitcnt lgkmcnt(0)
	s_setprio 0
	s_waitcnt lgkmcnt(0)
	v_mfma_f32_16x16x32_bf16 v[124:127], v[150:153], v[166:169], v[124:127]
	v_mfma_f32_16x16x32_bf16 v[120:123], v[158:161], v[166:169], v[120:123]
	v_mfma_f32_16x16x32_bf16 v[116:119], v[150:153], v[174:177], v[116:119]
	v_mfma_f32_16x16x32_bf16 v[112:115], v[158:161], v[174:177], v[112:115]
	v_mfma_f32_16x16x32_bf16 v[100:103], v[150:153], v[182:185], v[100:103]
	v_mfma_f32_16x16x32_bf16 v[96:99], v[158:161], v[182:185], v[96:99]
	v_mfma_f32_16x16x32_bf16 v[84:87], v[150:153], v[190:193], v[84:87]
	v_mfma_f32_16x16x32_bf16 v[80:83], v[158:161], v[190:193], v[80:83]
	v_mfma_f32_16x16x32_bf16 v[124:127], v[154:157], v[170:173], v[124:127]
	v_mfma_f32_16x16x32_bf16 v[120:123], v[162:165], v[170:173], v[120:123]
	v_mfma_f32_16x16x32_bf16 v[116:119], v[154:157], v[178:181], v[116:119]
	v_mfma_f32_16x16x32_bf16 v[112:115], v[162:165], v[178:181], v[112:115]
	v_mfma_f32_16x16x32_bf16 v[100:103], v[154:157], v[186:189], v[100:103]
	v_mfma_f32_16x16x32_bf16 v[96:99], v[162:165], v[186:189], v[96:99]
	v_mfma_f32_16x16x32_bf16 v[84:87], v[154:157], v[194:197], v[84:87]
	v_mfma_f32_16x16x32_bf16 v[80:83], v[162:165], v[194:197], v[80:83]
	s_setprio 1
	s_barrier
	s_add_i32 s38, 0, 0x1c000
	s_add_i32 s30, s70, s40
	v_add_u32_e32 v214, s38, v146
	v_lshl_add_u64 v[206:207], v[206:207], 0, s[14:15]
	s_mov_b32 m0, s30
	ds_read_b128 v[198:201], v214
	ds_read_b128 v[202:205], v214 offset:1024
	ds_read_b128 v[210:213], v214 offset:2048
	ds_read_b128 v[214:217], v214 offset:3072
	global_load_lds_dwordx4 v[206:207], off
	v_lshl_add_u64 v[206:207], v[218:219], 0, s[14:15]
	s_add_i32 m0, s30, 0x2000
	s_nop 0
	global_load_lds_dwordx4 v[206:207], off
	s_barrier
	s_waitcnt lgkmcnt(0)
	s_setprio 0
	s_waitcnt lgkmcnt(0)
	v_mfma_f32_16x16x32_bf16 v[108:111], v[198:201], v[166:169], v[108:111]
	v_mfma_f32_16x16x32_bf16 v[104:107], v[210:213], v[166:169], v[104:107]
	v_mfma_f32_16x16x32_bf16 v[92:95], v[198:201], v[174:177], v[92:95]
	v_mfma_f32_16x16x32_bf16 v[88:91], v[210:213], v[174:177], v[88:91]
	v_mfma_f32_16x16x32_bf16 v[76:79], v[198:201], v[182:185], v[76:79]
	v_mfma_f32_16x16x32_bf16 v[72:75], v[210:213], v[182:185], v[72:75]
	v_mfma_f32_16x16x32_bf16 v[68:71], v[198:201], v[190:193], v[68:71]
	v_mfma_f32_16x16x32_bf16 v[64:67], v[210:213], v[190:193], v[64:67]
	v_mfma_f32_16x16x32_bf16 v[108:111], v[202:205], v[170:173], v[108:111]
	v_mfma_f32_16x16x32_bf16 v[104:107], v[214:217], v[170:173], v[104:107]
	v_mfma_f32_16x16x32_bf16 v[92:95], v[202:205], v[178:181], v[92:95]
	v_mfma_f32_16x16x32_bf16 v[88:91], v[214:217], v[178:181], v[88:91]
	v_mfma_f32_16x16x32_bf16 v[76:79], v[202:205], v[186:189], v[76:79]
	v_mfma_f32_16x16x32_bf16 v[72:75], v[214:217], v[186:189], v[72:75]
	v_mfma_f32_16x16x32_bf16 v[68:71], v[202:205], v[194:197], v[68:71]
	v_mfma_f32_16x16x32_bf16 v[64:67], v[214:217], v[194:197], v[64:67]
	s_setprio 1
	s_mov_b32 m0, s52
	v_lshl_add_u64 v[206:207], v[220:221], 0, s[14:15]
	s_barrier
	ds_read_b128 v[166:169], v148 offset:49152
	ds_read_b128 v[170:173], v148 offset:50176
	ds_read_b128 v[174:177], v148 offset:51200
	ds_read_b128 v[178:181], v148 offset:52224
	ds_read_b128 v[182:185], v148 offset:53248
	ds_read_b128 v[186:189], v148 offset:54272
	ds_read_b128 v[190:193], v148 offset:55296
	ds_read_b128 v[194:197], v148 offset:56320
	global_load_lds_dwordx4 v[206:207], off
	v_lshl_add_u64 v[206:207], v[222:223], 0, s[14:15]
	s_mov_b32 m0, s53
	s_nop 0
	global_load_lds_dwordx4 v[206:207], off
	s_barrier
	s_waitcnt lgkmcnt(0)
	s_setprio 0
	s_waitcnt lgkmcnt(0)
	v_mfma_f32_16x16x32_bf16 v[60:63], v[150:153], v[166:169], v[60:63]
	v_mfma_f32_16x16x32_bf16 v[56:59], v[158:161], v[166:169], v[56:59]
	v_mfma_f32_16x16x32_bf16 v[52:55], v[150:153], v[174:177], v[52:55]
	v_mfma_f32_16x16x32_bf16 v[48:51], v[158:161], v[174:177], v[48:51]
	v_mfma_f32_16x16x32_bf16 v[36:39], v[150:153], v[182:185], v[36:39]
	v_mfma_f32_16x16x32_bf16 v[32:35], v[158:161], v[182:185], v[32:35]
	v_mfma_f32_16x16x32_bf16 v[20:23], v[150:153], v[190:193], v[20:23]
	v_mfma_f32_16x16x32_bf16 v[16:19], v[158:161], v[190:193], v[16:19]
	v_mfma_f32_16x16x32_bf16 v[60:63], v[154:157], v[170:173], v[60:63]
	v_mfma_f32_16x16x32_bf16 v[56:59], v[162:165], v[170:173], v[56:59]
	v_mfma_f32_16x16x32_bf16 v[52:55], v[154:157], v[178:181], v[52:55]
	v_mfma_f32_16x16x32_bf16 v[48:51], v[162:165], v[178:181], v[48:51]
	v_mfma_f32_16x16x32_bf16 v[36:39], v[154:157], v[186:189], v[36:39]
	v_mfma_f32_16x16x32_bf16 v[32:35], v[162:165], v[186:189], v[32:35]
	v_mfma_f32_16x16x32_bf16 v[20:23], v[154:157], v[194:197], v[20:23]
	v_mfma_f32_16x16x32_bf16 v[16:19], v[162:165], v[194:197], v[16:19]
	s_setprio 1
	s_barrier
	s_add_u32 s30, s36, 0xa0080
	s_addc_u32 s31, s37, 0
	s_add_i32 s36, s38, s40
	v_lshl_add_u64 v[150:151], s[30:31], 0, v[130:131]
	s_mov_b32 m0, s36
	s_nop 0
	global_load_lds_dwordx4 v[150:151], off
	v_lshl_add_u64 v[150:151], s[30:31], 0, v[134:135]
	s_add_i32 m0, s36, 0x2000
	s_nop 0
	global_load_lds_dwordx4 v[150:151], off
	s_waitcnt vmcnt(6)
	s_barrier
	s_setprio 0
	v_mfma_f32_16x16x32_bf16 v[44:47], v[198:201], v[166:169], v[44:47]
	v_mfma_f32_16x16x32_bf16 v[40:43], v[210:213], v[166:169], v[40:43]
	v_mfma_f32_16x16x32_bf16 v[28:31], v[198:201], v[174:177], v[28:31]
	v_mfma_f32_16x16x32_bf16 v[24:27], v[210:213], v[174:177], v[24:27]
	v_mfma_f32_16x16x32_bf16 v[12:15], v[198:201], v[182:185], v[12:15]
	v_mfma_f32_16x16x32_bf16 v[8:11], v[210:213], v[182:185], v[8:11]
	v_mfma_f32_16x16x32_bf16 v[4:7], v[198:201], v[190:193], v[4:7]
	v_mfma_f32_16x16x32_bf16 v[0:3], v[210:213], v[190:193], v[0:3]
	v_mfma_f32_16x16x32_bf16 v[44:47], v[202:205], v[170:173], v[44:47]
	v_mfma_f32_16x16x32_bf16 v[40:43], v[214:217], v[170:173], v[40:43]
	v_mfma_f32_16x16x32_bf16 v[28:31], v[202:205], v[178:181], v[28:31]
	v_mfma_f32_16x16x32_bf16 v[24:27], v[214:217], v[178:181], v[24:27]
	v_mfma_f32_16x16x32_bf16 v[12:15], v[202:205], v[186:189], v[12:15]
	v_mfma_f32_16x16x32_bf16 v[8:11], v[214:217], v[186:189], v[8:11]
	v_mfma_f32_16x16x32_bf16 v[4:7], v[202:205], v[194:197], v[4:7]
	v_mfma_f32_16x16x32_bf16 v[0:3], v[214:217], v[194:197], v[0:3]
	s_setprio 1
	s_add_i32 s69, s69, 2
	s_add_u32 s67, s67, 0x100
	s_addc_u32 s68, s68, 0
	s_cmp_gt_u32 s69, 37
	s_mov_b64 s[30:31], s[34:35]
	s_barrier
	s_cbranch_scc0 .LBB0_1402
	v_mov_b32_e32 v150, v145
	v_mov_b32_e32 v151, v144
	s_lshl_b32 s30, s63, 8
	s_add_i32 s30, s30, s49
	v_add_u32_e32 v150, s30, v150
	s_lshl_b32 s30, s66, 8
	s_or_b32 s30, s30, s51
	v_lshl_add_u32 v152, v151, 3, s30
	v_ashrrev_i32_e32 v151, 31, v150
	v_lshlrev_b64 v[150:151], 12, v[150:151]
	v_ashrrev_i32_e32 v153, 31, v152
	v_lshl_add_u64 v[150:151], s[10:11], 0, v[150:151]
	v_lshl_add_u64 v[150:151], v[152:153], 1, v[150:151]
	v_cvt_pk_bf16_f32 v108, v108, v109
	v_cvt_pk_bf16_f32 v109, v110, v111
	v_cvt_pk_bf16_f32 v110, v104, v105
	v_cvt_pk_bf16_f32 v111, v106, v107
	global_store_dwordx4 v[150:151], v[108:111], off offset:256
	v_cvt_pk_bf16_f32 v92, v92, v93
	v_cvt_pk_bf16_f32 v93, v94, v95
	v_add_co_u32_e32 v110, vcc, s48, v150
	v_lshl_add_u64 v[108:109], v[150:151], 0, s[18:19]
	s_nop 0
	v_addc_co_u32_e32 v111, vcc, 0, v151, vcc
	v_cvt_pk_bf16_f32 v94, v88, v89
	v_cvt_pk_bf16_f32 v95, v90, v91
	global_store_dwordx4 v[108:109], v[92:95], off offset:256
	v_cvt_pk_bf16_f32 v76, v76, v77
	v_cvt_pk_bf16_f32 v77, v78, v79
	v_add_co_u32_e32 v94, vcc, s56, v150
	v_lshl_add_u64 v[92:93], v[150:151], 0, s[20:21]
	s_nop 0
	v_addc_co_u32_e32 v95, vcc, 0, v151, vcc
	v_cvt_pk_bf16_f32 v78, v72, v73
	v_cvt_pk_bf16_f32 v79, v74, v75
	global_store_dwordx4 v[92:93], v[76:79], off offset:256
	v_cvt_pk_bf16_f32 v60, v60, v61
	v_cvt_pk_bf16_f32 v61, v62, v63
	v_add_co_u32_e32 v78, vcc, s57, v150
	v_cvt_pk_bf16_f32 v62, v56, v57
	s_nop 0
	v_addc_co_u32_e32 v79, vcc, 0, v151, vcc
	v_add_co_u32_e32 v56, vcc, s59, v150
	v_cvt_pk_bf16_f32 v68, v68, v69
	v_cvt_pk_bf16_f32 v69, v70, v71
	v_cvt_pk_bf16_f32 v70, v64, v65
	v_lshl_add_u64 v[64:65], v[150:151], 0, s[24:25]
	v_addc_co_u32_e32 v57, vcc, 0, v151, vcc
	v_cvt_pk_bf16_f32 v44, v44, v45
	v_cvt_pk_bf16_f32 v45, v46, v47
	v_cvt_pk_bf16_f32 v46, v40, v41
	v_cvt_pk_bf16_f32 v47, v42, v43
	global_store_dwordx4 v[64:65], v[44:47], off offset:256
	v_cvt_pk_bf16_f32 v28, v28, v29
	v_cvt_pk_bf16_f32 v29, v30, v31
	v_add_co_u32_e32 v46, vcc, s60, v150
	v_lshl_add_u64 v[44:45], v[150:151], 0, s[26:27]
	s_nop 0
	v_addc_co_u32_e32 v47, vcc, 0, v151, vcc
	v_cvt_pk_bf16_f32 v30, v24, v25
	v_cvt_pk_bf16_f32 v31, v26, v27
	global_store_dwordx4 v[44:45], v[28:31], off offset:256
	v_cvt_pk_bf16_f32 v12, v12, v13
	v_cvt_pk_bf16_f32 v13, v14, v15
	v_add_co_u32_e32 v30, vcc, s61, v150
	v_lshl_add_u64 v[28:29], v[150:151], 0, s[8:9]
	s_nop 0
	v_addc_co_u32_e32 v31, vcc, 0, v151, vcc
	v_cvt_pk_bf16_f32 v14, v8, v9
	v_cvt_pk_bf16_f32 v15, v10, v11
	global_store_dwordx4 v[28:29], v[12:15], off offset:256
	v_cvt_pk_bf16_f32 v124, v124, v125
	v_cvt_pk_bf16_f32 v125, v126, v127
	v_add_co_u32_e32 v14, vcc, s62, v150
	v_cvt_pk_bf16_f32 v126, v120, v121
	s_nop 0
	v_addc_co_u32_e32 v15, vcc, 0, v151, vcc
	v_cvt_pk_bf16_f32 v127, v122, v123
	v_cvt_pk_bf16_f32 v104, v116, v117
	v_cvt_pk_bf16_f32 v105, v118, v119
	v_cvt_pk_bf16_f32 v106, v112, v113
	v_cvt_pk_bf16_f32 v107, v114, v115
	v_cvt_pk_bf16_f32 v88, v100, v101
	v_cvt_pk_bf16_f32 v89, v102, v103
	v_cvt_pk_bf16_f32 v90, v96, v97
	v_cvt_pk_bf16_f32 v91, v98, v99
	v_lshl_add_u64 v[76:77], v[150:151], 0, s[22:23]
	v_cvt_pk_bf16_f32 v72, v84, v85
	v_cvt_pk_bf16_f32 v73, v86, v87
	v_cvt_pk_bf16_f32 v74, v80, v81
	v_cvt_pk_bf16_f32 v75, v82, v83
	v_cvt_pk_bf16_f32 v71, v66, v67
	v_cvt_pk_bf16_f32 v63, v58, v59
	v_cvt_pk_bf16_f32 v40, v52, v53
	v_cvt_pk_bf16_f32 v41, v54, v55
	v_cvt_pk_bf16_f32 v42, v48, v49
	v_cvt_pk_bf16_f32 v43, v50, v51
	v_cvt_pk_bf16_f32 v24, v36, v37
	v_cvt_pk_bf16_f32 v25, v38, v39
	v_cvt_pk_bf16_f32 v26, v32, v33
	v_cvt_pk_bf16_f32 v27, v34, v35
	v_lshl_add_u64 v[12:13], v[150:151], 0, s[28:29]
	v_cvt_pk_bf16_f32 v8, v20, v21
	v_cvt_pk_bf16_f32 v9, v22, v23
	v_cvt_pk_bf16_f32 v10, v16, v17
	v_cvt_pk_bf16_f32 v11, v18, v19
	v_cvt_pk_bf16_f32 v4, v4, v5
	v_cvt_pk_bf16_f32 v5, v6, v7
	v_cvt_pk_bf16_f32 v6, v0, v1
	v_cvt_pk_bf16_f32 v7, v2, v3
	s_and_b64 vcc, exec, s[2:3]
	s_mov_b32 s66, s64
	s_mov_b32 s63, s65
	s_mov_b64 s[34:35], s[6:7]
	s_mov_b64 s[30:31], s[4:5]
	global_store_dwordx4 v[150:151], v[124:127], off
	global_store_dwordx4 v[110:111], v[104:107], off
	global_store_dwordx4 v[94:95], v[88:91], off
	global_store_dwordx4 v[78:79], v[72:75], off
	global_store_dwordx4 v[76:77], v[68:71], off offset:256
	global_store_dwordx4 v[56:57], v[60:63], off
	global_store_dwordx4 v[46:47], v[40:43], off
	global_store_dwordx4 v[30:31], v[24:27], off
	global_store_dwordx4 v[14:15], v[8:11], off
	global_store_dwordx4 v[12:13], v[4:7], off offset:256
	s_cbranch_vccz .LBB0_1391
	s_waitcnt vmcnt(0)
	s_cmpk_gt_u32 s33, 0xff
	s_cbranch_scc1 .LBB0_1406
	s_barrier
